# GEMM loops: compute-segment tail set-up moved to the end of the same phase's memory cluster (before its leading barrier); duplicate lgkmcnt(0) dropped
# baseline (speedup 1.0000x reference)
.LBB0_37:
	s_add_i32 s69, s48, 2
	s_add_u32 s46, s0, 0x100
	s_addc_u32 s47, s1, 0
	s_add_i32 s70, 0, 0x10000
	v_add_u32_e32 v156, s70, v153
	ds_read_b128 v[140:143], v156
	ds_read_b128 v[144:147], v156 offset:1024
	ds_read_b128 v[148:151], v156 offset:2048
	ds_read_b128 v[168:171], v156 offset:3072
	s_cmp_eq_u32 s12, s48
	s_cselect_b32 s48, s44, s13
	s_cselect_b32 s51, s43, s47
	s_cselect_b32 s50, s42, s46
	s_cselect_b32 s49, s45, s68
	v_lshl_add_u64 v[156:157], s[0:1], 0, v[136:137]
	s_add_i32 m0, s53, 0xc000
	ds_read_b128 v[172:175], v155
	ds_read_b128 v[176:179], v155 offset:1024
	ds_read_b128 v[180:183], v155 offset:2048
	ds_read_b128 v[184:187], v155 offset:3072
	ds_read_b128 v[188:191], v155 offset:4096
	ds_read_b128 v[192:195], v155 offset:5120
	ds_read_b128 v[196:199], v155 offset:6144
	ds_read_b128 v[224:227], v155 offset:7168
	global_load_lds_dwordx4 v[156:157], off
	v_lshl_add_u64 v[156:157], s[0:1], 0, v[138:139]
	s_add_i32 m0, s53, 0xe000
	s_nop 0
	global_load_lds_dwordx4 v[156:157], off
	s_waitcnt lgkmcnt(8)
	s_barrier
	s_waitcnt lgkmcnt(0)
	v_mfma_f32_16x16x32_bf16 v[126:129], v[140:143], v[172:175], v[126:129]
	v_mfma_f32_16x16x32_bf16 v[122:125], v[148:151], v[172:175], v[122:125]
	v_mfma_f32_16x16x32_bf16 v[110:113], v[140:143], v[180:183], v[110:113]
	v_mfma_f32_16x16x32_bf16 v[106:109], v[148:151], v[180:183], v[106:109]
	v_mfma_f32_16x16x32_bf16 v[94:97], v[140:143], v[188:191], v[94:97]
	v_mfma_f32_16x16x32_bf16 v[90:93], v[148:151], v[188:191], v[90:93]
	v_mfma_f32_16x16x32_bf16 v[78:81], v[140:143], v[196:199], v[78:81]
	v_mfma_f32_16x16x32_bf16 v[74:77], v[148:151], v[196:199], v[74:77]
	v_mfma_f32_16x16x32_bf16 v[126:129], v[144:147], v[176:179], v[126:129]
	v_mfma_f32_16x16x32_bf16 v[122:125], v[168:171], v[176:179], v[122:125]
	v_mfma_f32_16x16x32_bf16 v[110:113], v[144:147], v[184:187], v[110:113]
	v_mfma_f32_16x16x32_bf16 v[106:109], v[168:171], v[184:187], v[106:109]
	v_mfma_f32_16x16x32_bf16 v[94:97], v[144:147], v[192:195], v[94:97]
	v_mfma_f32_16x16x32_bf16 v[90:93], v[168:171], v[192:195], v[90:93]
	v_mfma_f32_16x16x32_bf16 v[78:81], v[144:147], v[224:227], v[78:81]
	v_mfma_f32_16x16x32_bf16 v[74:77], v[168:171], v[224:227], v[74:77]
	s_barrier
	s_add_i32 s71, 0, 0x14000
	v_add_u32_e32 v156, s71, v153
	s_add_i32 s0, s70, s52
	ds_read_b128 v[228:231], v156
	ds_read_b128 v[232:235], v156 offset:1024
	ds_read_b128 v[236:239], v156 offset:2048
	ds_read_b128 v[240:243], v156 offset:3072
	s_add_u32 s76, s48, s94
	s_addc_u32 s77, s49, s95
	s_mov_b32 m0, s0
	s_nop 0
	global_load_lds_dwordx4 v0, s[48:49]
	s_add_i32 m0, s0, 0x2000
	s_nop 0
	global_load_lds_dwordx4 v130, s[48:49]
	s_mov_b32 m0, s53
	s_add_u32 s78, s50, s94
	s_addc_u32 s79, s51, s95
	s_barrier
	s_waitcnt lgkmcnt(0)
	v_mfma_f32_16x16x32_bf16 v[118:121], v[228:231], v[172:175], v[118:121]
	v_mfma_f32_16x16x32_bf16 v[114:117], v[236:239], v[172:175], v[114:117]
	v_mfma_f32_16x16x32_bf16 v[102:105], v[228:231], v[180:183], v[102:105]
	v_mfma_f32_16x16x32_bf16 v[98:101], v[236:239], v[180:183], v[98:101]
	v_mfma_f32_16x16x32_bf16 v[86:89], v[228:231], v[188:191], v[86:89]
	v_mfma_f32_16x16x32_bf16 v[82:85], v[236:239], v[188:191], v[82:85]
	v_mfma_f32_16x16x32_bf16 v[70:73], v[228:231], v[196:199], v[70:73]
	v_mfma_f32_16x16x32_bf16 v[66:69], v[236:239], v[196:199], v[66:69]
	v_mfma_f32_16x16x32_bf16 v[118:121], v[232:235], v[176:179], v[118:121]
	v_mfma_f32_16x16x32_bf16 v[114:117], v[240:243], v[176:179], v[114:117]
	v_mfma_f32_16x16x32_bf16 v[102:105], v[232:235], v[184:187], v[102:105]
	v_mfma_f32_16x16x32_bf16 v[98:101], v[240:243], v[184:187], v[98:101]
	v_mfma_f32_16x16x32_bf16 v[86:89], v[232:235], v[192:195], v[86:89]
	v_mfma_f32_16x16x32_bf16 v[82:85], v[240:243], v[192:195], v[82:85]
	v_mfma_f32_16x16x32_bf16 v[70:73], v[232:235], v[224:227], v[70:73]
	v_mfma_f32_16x16x32_bf16 v[66:69], v[240:243], v[224:227], v[66:69]
	s_barrier
	ds_read_b128 v[172:175], v155 offset:16384
	ds_read_b128 v[176:179], v155 offset:17408
	ds_read_b128 v[180:183], v155 offset:18432
	ds_read_b128 v[184:187], v155 offset:19456
	ds_read_b128 v[188:191], v155 offset:20480
	ds_read_b128 v[192:195], v155 offset:21504
	ds_read_b128 v[196:199], v155 offset:22528
	ds_read_b128 v[224:227], v155 offset:23552
	global_load_lds_dwordx4 v134, s[50:51]
	s_mov_b32 m0, s54
	s_nop 0
	global_load_lds_dwordx4 v132, s[50:51]
	s_barrier
	s_waitcnt lgkmcnt(0)
	v_mfma_f32_16x16x32_bf16 v[62:65], v[140:143], v[172:175], v[62:65]
	v_mfma_f32_16x16x32_bf16 v[58:61], v[148:151], v[172:175], v[58:61]
	v_mfma_f32_16x16x32_bf16 v[46:49], v[140:143], v[180:183], v[46:49]
	v_mfma_f32_16x16x32_bf16 v[42:45], v[148:151], v[180:183], v[42:45]
	v_mfma_f32_16x16x32_bf16 v[30:33], v[140:143], v[188:191], v[30:33]
	v_mfma_f32_16x16x32_bf16 v[26:29], v[148:151], v[188:191], v[26:29]
	v_mfma_f32_16x16x32_bf16 v[14:17], v[140:143], v[196:199], v[14:17]
	v_mfma_f32_16x16x32_bf16 v[10:13], v[148:151], v[196:199], v[10:13]
	v_mfma_f32_16x16x32_bf16 v[62:65], v[144:147], v[176:179], v[62:65]
	v_mfma_f32_16x16x32_bf16 v[58:61], v[168:171], v[176:179], v[58:61]
	v_mfma_f32_16x16x32_bf16 v[46:49], v[144:147], v[184:187], v[46:49]
	v_mfma_f32_16x16x32_bf16 v[42:45], v[168:171], v[184:187], v[42:45]
	v_mfma_f32_16x16x32_bf16 v[30:33], v[144:147], v[192:195], v[30:33]
	v_mfma_f32_16x16x32_bf16 v[26:29], v[168:171], v[192:195], v[26:29]
	v_mfma_f32_16x16x32_bf16 v[14:17], v[144:147], v[224:227], v[14:17]
	v_mfma_f32_16x16x32_bf16 v[10:13], v[168:171], v[224:227], v[10:13]
	s_barrier
	s_add_u32 s0, s48, 0x160000
	s_addc_u32 s1, s49, 0
	s_add_i32 s70, s71, s52
	s_mov_b32 m0, s70
	s_nop 0
	global_load_lds_dwordx4 v0, s[0:1]
	s_add_i32 m0, s70, 0x2000
	s_nop 0
	global_load_lds_dwordx4 v130, s[0:1]
	s_add_i32 s70, 0, 0x18000
	v_add_u32_e32 v161, s70, v153
	s_waitcnt vmcnt(6)
	s_barrier
	v_mfma_f32_16x16x32_bf16 v[54:57], v[228:231], v[172:175], v[54:57]
	v_mfma_f32_16x16x32_bf16 v[50:53], v[236:239], v[172:175], v[50:53]
	v_mfma_f32_16x16x32_bf16 v[38:41], v[228:231], v[180:183], v[38:41]
	v_mfma_f32_16x16x32_bf16 v[34:37], v[236:239], v[180:183], v[34:37]
	v_mfma_f32_16x16x32_bf16 v[22:25], v[228:231], v[188:191], v[22:25]
	v_mfma_f32_16x16x32_bf16 v[18:21], v[236:239], v[188:191], v[18:21]
	v_mfma_f32_16x16x32_bf16 v[6:9], v[228:231], v[196:199], v[6:9]
	v_mfma_f32_16x16x32_bf16 v[2:5], v[236:239], v[196:199], v[2:5]
	v_mfma_f32_16x16x32_bf16 v[54:57], v[232:235], v[176:179], v[54:57]
	v_mfma_f32_16x16x32_bf16 v[50:53], v[240:243], v[176:179], v[50:53]
	v_mfma_f32_16x16x32_bf16 v[38:41], v[232:235], v[184:187], v[38:41]
	v_mfma_f32_16x16x32_bf16 v[34:37], v[240:243], v[184:187], v[34:37]
	v_mfma_f32_16x16x32_bf16 v[22:25], v[232:235], v[192:195], v[22:25]
	v_mfma_f32_16x16x32_bf16 v[18:21], v[240:243], v[192:195], v[18:21]
	v_mfma_f32_16x16x32_bf16 v[6:9], v[232:235], v[224:227], v[6:9]
	v_mfma_f32_16x16x32_bf16 v[2:5], v[240:243], v[224:227], v[2:5]
	s_barrier
	ds_read_b128 v[140:143], v161
	ds_read_b128 v[144:147], v161 offset:1024
	ds_read_b128 v[148:151], v161 offset:2048
	ds_read_b128 v[168:171], v161 offset:3072
	s_add_u32 s0, s50, 0x2c0000
	s_addc_u32 s1, s51, 0
	s_mov_b32 m0, s55
	ds_read_b128 v[172:175], v155 offset:32768
	ds_read_b128 v[176:179], v155 offset:33792
	ds_read_b128 v[180:183], v155 offset:34816
	ds_read_b128 v[184:187], v155 offset:35840
	ds_read_b128 v[188:191], v155 offset:36864
	ds_read_b128 v[192:195], v155 offset:37888
	ds_read_b128 v[196:199], v155 offset:38912
	ds_read_b128 v[224:227], v155 offset:39936
	global_load_lds_dwordx4 v134, s[0:1]
	s_mov_b32 m0, s56
	s_nop 0
	global_load_lds_dwordx4 v132, s[0:1]
	s_waitcnt lgkmcnt(8)
	s_barrier
	s_waitcnt lgkmcnt(0)
	v_mfma_f32_16x16x32_bf16 v[126:129], v[140:143], v[172:175], v[126:129]
	v_mfma_f32_16x16x32_bf16 v[122:125], v[148:151], v[172:175], v[122:125]
	v_mfma_f32_16x16x32_bf16 v[110:113], v[140:143], v[180:183], v[110:113]
	v_mfma_f32_16x16x32_bf16 v[106:109], v[148:151], v[180:183], v[106:109]
	v_mfma_f32_16x16x32_bf16 v[94:97], v[140:143], v[188:191], v[94:97]
	v_mfma_f32_16x16x32_bf16 v[90:93], v[148:151], v[188:191], v[90:93]
	v_mfma_f32_16x16x32_bf16 v[78:81], v[140:143], v[196:199], v[78:81]
	v_mfma_f32_16x16x32_bf16 v[74:77], v[148:151], v[196:199], v[74:77]
	v_mfma_f32_16x16x32_bf16 v[126:129], v[144:147], v[176:179], v[126:129]
	v_mfma_f32_16x16x32_bf16 v[122:125], v[168:171], v[176:179], v[122:125]
	v_mfma_f32_16x16x32_bf16 v[110:113], v[144:147], v[184:187], v[110:113]
	v_mfma_f32_16x16x32_bf16 v[106:109], v[168:171], v[184:187], v[106:109]
	v_mfma_f32_16x16x32_bf16 v[94:97], v[144:147], v[192:195], v[94:97]
	v_mfma_f32_16x16x32_bf16 v[90:93], v[168:171], v[192:195], v[90:93]
	v_mfma_f32_16x16x32_bf16 v[78:81], v[144:147], v[224:227], v[78:81]
	v_mfma_f32_16x16x32_bf16 v[74:77], v[168:171], v[224:227], v[74:77]
	s_barrier
	s_add_i32 s50, 0, 0x1c000
	s_add_i32 s0, s70, s52
	v_add_u32_e32 v161, s50, v153
	s_mov_b32 m0, s0
	ds_read_b128 v[228:231], v161
	ds_read_b128 v[232:235], v161 offset:1024
	ds_read_b128 v[236:239], v161 offset:2048
	ds_read_b128 v[240:243], v161 offset:3072
	global_load_lds_dwordx4 v0, s[76:77]
	s_add_i32 m0, s0, 0x2000
	s_nop 0
	global_load_lds_dwordx4 v130, s[76:77]
	s_mov_b32 m0, s57
	s_barrier
	s_waitcnt lgkmcnt(0)
	v_mfma_f32_16x16x32_bf16 v[118:121], v[228:231], v[172:175], v[118:121]
	v_mfma_f32_16x16x32_bf16 v[114:117], v[236:239], v[172:175], v[114:117]
	v_mfma_f32_16x16x32_bf16 v[102:105], v[228:231], v[180:183], v[102:105]
	v_mfma_f32_16x16x32_bf16 v[98:101], v[236:239], v[180:183], v[98:101]
	v_mfma_f32_16x16x32_bf16 v[86:89], v[228:231], v[188:191], v[86:89]
	v_mfma_f32_16x16x32_bf16 v[82:85], v[236:239], v[188:191], v[82:85]
	v_mfma_f32_16x16x32_bf16 v[70:73], v[228:231], v[196:199], v[70:73]
	v_mfma_f32_16x16x32_bf16 v[66:69], v[236:239], v[196:199], v[66:69]
	v_mfma_f32_16x16x32_bf16 v[118:121], v[232:235], v[176:179], v[118:121]
	v_mfma_f32_16x16x32_bf16 v[114:117], v[240:243], v[176:179], v[114:117]
	v_mfma_f32_16x16x32_bf16 v[102:105], v[232:235], v[184:187], v[102:105]
	v_mfma_f32_16x16x32_bf16 v[98:101], v[240:243], v[184:187], v[98:101]
	v_mfma_f32_16x16x32_bf16 v[86:89], v[232:235], v[192:195], v[86:89]
	v_mfma_f32_16x16x32_bf16 v[82:85], v[240:243], v[192:195], v[82:85]
	v_mfma_f32_16x16x32_bf16 v[70:73], v[232:235], v[224:227], v[70:73]
	v_mfma_f32_16x16x32_bf16 v[66:69], v[240:243], v[224:227], v[66:69]
	s_barrier
	ds_read_b128 v[172:175], v155 offset:49152
	ds_read_b128 v[176:179], v155 offset:50176
	ds_read_b128 v[180:183], v155 offset:51200
	ds_read_b128 v[184:187], v155 offset:52224
	ds_read_b128 v[188:191], v155 offset:53248
	ds_read_b128 v[192:195], v155 offset:54272
	ds_read_b128 v[196:199], v155 offset:55296
	ds_read_b128 v[224:227], v155 offset:56320
	global_load_lds_dwordx4 v134, s[78:79]
	s_mov_b32 m0, s58
	s_nop 0
	global_load_lds_dwordx4 v132, s[78:79]
	s_barrier
	s_waitcnt lgkmcnt(0)
	v_mfma_f32_16x16x32_bf16 v[62:65], v[140:143], v[172:175], v[62:65]
	v_mfma_f32_16x16x32_bf16 v[58:61], v[148:151], v[172:175], v[58:61]
	v_mfma_f32_16x16x32_bf16 v[46:49], v[140:143], v[180:183], v[46:49]
	v_mfma_f32_16x16x32_bf16 v[42:45], v[148:151], v[180:183], v[42:45]
	v_mfma_f32_16x16x32_bf16 v[30:33], v[140:143], v[188:191], v[30:33]
	v_mfma_f32_16x16x32_bf16 v[26:29], v[148:151], v[188:191], v[26:29]
	v_mfma_f32_16x16x32_bf16 v[14:17], v[140:143], v[196:199], v[14:17]
	v_mfma_f32_16x16x32_bf16 v[10:13], v[148:151], v[196:199], v[10:13]
	v_mfma_f32_16x16x32_bf16 v[62:65], v[144:147], v[176:179], v[62:65]
	v_mfma_f32_16x16x32_bf16 v[58:61], v[168:171], v[176:179], v[58:61]
	v_mfma_f32_16x16x32_bf16 v[46:49], v[144:147], v[184:187], v[46:49]
	v_mfma_f32_16x16x32_bf16 v[42:45], v[168:171], v[184:187], v[42:45]
	v_mfma_f32_16x16x32_bf16 v[30:33], v[144:147], v[192:195], v[30:33]
	v_mfma_f32_16x16x32_bf16 v[26:29], v[168:171], v[192:195], v[26:29]
	v_mfma_f32_16x16x32_bf16 v[14:17], v[144:147], v[224:227], v[14:17]
	v_mfma_f32_16x16x32_bf16 v[10:13], v[168:171], v[224:227], v[10:13]
	s_barrier
	s_add_u32 s0, s48, 0x160080
	s_addc_u32 s1, s49, 0
	s_add_i32 s48, s50, s52
	s_mov_b32 m0, s48
	s_nop 0
	global_load_lds_dwordx4 v0, s[0:1]
	s_add_i32 m0, s48, 0x2000
	s_nop 0
	global_load_lds_dwordx4 v130, s[0:1]
	s_add_u32 s13, s13, 0x100
	s_addc_u32 s68, s68, 0
	s_mov_b64 s[0:1], s[46:47]
	s_mov_b32 s48, s69
	s_waitcnt vmcnt(6)
	s_barrier
	v_mfma_f32_16x16x32_bf16 v[54:57], v[228:231], v[172:175], v[54:57]
	v_mfma_f32_16x16x32_bf16 v[50:53], v[236:239], v[172:175], v[50:53]
	v_mfma_f32_16x16x32_bf16 v[38:41], v[228:231], v[180:183], v[38:41]
	v_mfma_f32_16x16x32_bf16 v[34:37], v[236:239], v[180:183], v[34:37]
	v_mfma_f32_16x16x32_bf16 v[22:25], v[228:231], v[188:191], v[22:25]
	v_mfma_f32_16x16x32_bf16 v[18:21], v[236:239], v[188:191], v[18:21]
	v_mfma_f32_16x16x32_bf16 v[6:9], v[228:231], v[196:199], v[6:9]
	v_mfma_f32_16x16x32_bf16 v[2:5], v[236:239], v[196:199], v[2:5]
	v_mfma_f32_16x16x32_bf16 v[54:57], v[232:235], v[176:179], v[54:57]
	v_mfma_f32_16x16x32_bf16 v[50:53], v[240:243], v[176:179], v[50:53]
	v_mfma_f32_16x16x32_bf16 v[38:41], v[232:235], v[184:187], v[38:41]
	v_mfma_f32_16x16x32_bf16 v[34:37], v[240:243], v[184:187], v[34:37]
	v_mfma_f32_16x16x32_bf16 v[22:25], v[232:235], v[192:195], v[22:25]
	v_mfma_f32_16x16x32_bf16 v[18:21], v[240:243], v[192:195], v[18:21]
	v_mfma_f32_16x16x32_bf16 v[6:9], v[232:235], v[224:227], v[6:9]
	v_mfma_f32_16x16x32_bf16 v[2:5], v[240:243], v[224:227], v[2:5]
	s_barrier
	s_cmp_ge_i32 s69, s39
	s_cbranch_scc0 .LBB0_37
	s_cmp_eq_u32 s65, 2
	s_cbranch_scc1 .Lepi10_orig
	v_readlane_b32 s90, v255, 17
	v_readlane_b32 s91, v255, 18
	v_readlane_b32 s96, v255, 19
	v_readlane_b32 s97, v255, 20
	v_lshl_or_b32 v156, s66, 8, v154
	v_lshlrev_b32_e32 v156, 2, v156
	v_lshl_add_u32 v157, v152, 13, v156
	s_lshl_b32 s72, s67, 21
	s_add_u32 s74, s22, s72
	s_addc_u32 s75, s23, 0
	s_add_u32 s76, s22, s72
	s_addc_u32 s77, s23, 0
	s_lshr_b32 s73, s67, 3
	s_mul_i32 s73, s73, 0xc000
	s_add_u32 s73, s73, 0xa000
	s_add_u32 s70, s90, s73
	s_addc_u32 s71, s91, 0
	global_load_dwordx4 v[140:143], v156, s[70:71]
	global_load_dwordx4 v[144:147], v156, s[70:71] offset:64
	global_load_dwordx4 v[148:151], v156, s[70:71] offset:512
	global_load_dwordx4 v[168:171], v156, s[70:71] offset:576
	global_load_dwordx4 v[224:227], v157, s[74:75] nt
	global_load_dwordx4 v[228:231], v157, s[74:75] offset:64 nt
	global_load_dwordx4 v[232:235], v157, s[74:75] offset:512 nt
	global_load_dwordx4 v[236:239], v157, s[74:75] offset:576 nt
	s_add_u32 s74, s74, 0x20000
	s_addc_u32 s75, s75, 0
	global_load_dwordx4 v[240:243], v157, s[74:75] nt
	global_load_dwordx4 v[244:247], v157, s[74:75] offset:64 nt
	s_waitcnt vmcnt(5)
	v_pk_fma_f32 v[128:129], v[128:129], v[142:143], v[226:227]
	v_pk_fma_f32 v[126:127], v[126:127], v[140:141], v[224:225]
	global_store_dwordx4 v157, v[126:129], s[76:77] nt
	global_load_dwordx4 v[224:227], v157, s[74:75] offset:512 nt
	s_waitcnt vmcnt(6)
	v_pk_fma_f32 v[124:125], v[124:125], v[146:147], v[230:231]
	v_pk_fma_f32 v[122:123], v[122:123], v[144:145], v[228:229]
	global_store_dwordx4 v157, v[122:125], s[76:77] offset:64 nt
	global_load_dwordx4 v[228:231], v157, s[74:75] offset:576 nt
	s_waitcnt vmcnt(7)
	v_pk_fma_f32 v[120:121], v[120:121], v[150:151], v[234:235]
	v_pk_fma_f32 v[118:119], v[118:119], v[148:149], v[232:233]
	global_store_dwordx4 v157, v[118:121], s[76:77] offset:512 nt
	s_add_u32 s74, s74, 0x20000
	s_addc_u32 s75, s75, 0
	global_load_dwordx4 v[232:235], v157, s[74:75] nt
	s_waitcnt vmcnt(8)
	v_pk_fma_f32 v[116:117], v[116:117], v[170:171], v[238:239]
	v_pk_fma_f32 v[114:115], v[114:115], v[168:169], v[236:237]
	global_store_dwordx4 v157, v[114:117], s[76:77] offset:576 nt
	global_load_dwordx4 v[236:239], v157, s[74:75] offset:64 nt
	s_add_u32 s76, s76, 0x20000
	s_addc_u32 s77, s77, 0
	s_waitcnt vmcnt(9)
	v_pk_fma_f32 v[112:113], v[112:113], v[142:143], v[242:243]
	v_pk_fma_f32 v[110:111], v[110:111], v[140:141], v[240:241]
	global_store_dwordx4 v157, v[110:113], s[76:77] nt
	global_load_dwordx4 v[240:243], v157, s[74:75] offset:512 nt
	s_waitcnt vmcnt(10)
	v_pk_fma_f32 v[108:109], v[108:109], v[146:147], v[246:247]
	v_pk_fma_f32 v[106:107], v[106:107], v[144:145], v[244:245]
	global_store_dwordx4 v157, v[106:109], s[76:77] offset:64 nt
	global_load_dwordx4 v[244:247], v157, s[74:75] offset:576 nt
	s_waitcnt vmcnt(10)
	v_pk_fma_f32 v[104:105], v[104:105], v[150:151], v[226:227]
	v_pk_fma_f32 v[102:103], v[102:103], v[148:149], v[224:225]
	global_store_dwordx4 v157, v[102:105], s[76:77] offset:512 nt
	s_add_u32 s74, s74, 0x20000
	s_addc_u32 s75, s75, 0
	global_load_dwordx4 v[224:227], v157, s[74:75] nt
	s_waitcnt vmcnt(10)
	v_pk_fma_f32 v[100:101], v[100:101], v[170:171], v[230:231]
	v_pk_fma_f32 v[98:99], v[98:99], v[168:169], v[228:229]
	global_store_dwordx4 v157, v[98:101], s[76:77] offset:576 nt
	global_load_dwordx4 v[228:231], v157, s[74:75] offset:64 nt
	s_add_u32 s76, s76, 0x20000
	s_addc_u32 s77, s77, 0
	s_waitcnt vmcnt(10)
	v_pk_fma_f32 v[96:97], v[96:97], v[142:143], v[234:235]
	v_pk_fma_f32 v[94:95], v[94:95], v[140:141], v[232:233]
	global_store_dwordx4 v157, v[94:97], s[76:77] nt
	global_load_dwordx4 v[232:235], v157, s[74:75] offset:512 nt
	s_waitcnt vmcnt(10)
	v_pk_fma_f32 v[92:93], v[92:93], v[146:147], v[238:239]
	v_pk_fma_f32 v[90:91], v[90:91], v[144:145], v[236:237]
	global_store_dwordx4 v157, v[90:93], s[76:77] offset:64 nt
	global_load_dwordx4 v[236:239], v157, s[74:75] offset:576 nt
	s_waitcnt vmcnt(10)
	v_pk_fma_f32 v[88:89], v[88:89], v[150:151], v[242:243]
	v_pk_fma_f32 v[86:87], v[86:87], v[148:149], v[240:241]
	global_store_dwordx4 v157, v[86:89], s[76:77] offset:512 nt
	s_add_u32 s74, s74, 0xa0000
	s_addc_u32 s75, s75, 0
	global_load_dwordx4 v[240:243], v157, s[74:75] nt
	s_waitcnt vmcnt(10)
	v_pk_fma_f32 v[84:85], v[84:85], v[170:171], v[246:247]
	v_pk_fma_f32 v[82:83], v[82:83], v[168:169], v[244:245]
	global_store_dwordx4 v157, v[82:85], s[76:77] offset:576 nt
	global_load_dwordx4 v[244:247], v157, s[74:75] offset:64 nt
	s_add_u32 s76, s76, 0x20000
	s_addc_u32 s77, s77, 0
	s_waitcnt vmcnt(10)
	v_pk_fma_f32 v[80:81], v[80:81], v[142:143], v[226:227]
	v_pk_fma_f32 v[78:79], v[78:79], v[140:141], v[224:225]
	global_store_dwordx4 v157, v[78:81], s[76:77] nt
	global_load_dwordx4 v[224:227], v157, s[74:75] offset:512 nt
	s_waitcnt vmcnt(10)
	v_pk_fma_f32 v[76:77], v[76:77], v[146:147], v[230:231]
	v_pk_fma_f32 v[74:75], v[74:75], v[144:145], v[228:229]
	global_store_dwordx4 v157, v[74:77], s[76:77] offset:64 nt
	global_load_dwordx4 v[228:231], v157, s[74:75] offset:576 nt
	s_waitcnt vmcnt(10)
	v_pk_fma_f32 v[72:73], v[72:73], v[150:151], v[234:235]
	v_pk_fma_f32 v[70:71], v[70:71], v[148:149], v[232:233]
	global_store_dwordx4 v157, v[70:73], s[76:77] offset:512 nt
	s_add_u32 s74, s74, 0x20000
	s_addc_u32 s75, s75, 0
	global_load_dwordx4 v[232:235], v157, s[74:75] nt
	s_waitcnt vmcnt(10)
	v_pk_fma_f32 v[68:69], v[68:69], v[170:171], v[238:239]
	v_pk_fma_f32 v[66:67], v[66:67], v[168:169], v[236:237]
	global_store_dwordx4 v157, v[66:69], s[76:77] offset:576 nt
	global_load_dwordx4 v[236:239], v157, s[74:75] offset:64 nt
	s_add_u32 s76, s76, 0xa0000
	s_addc_u32 s77, s77, 0
	s_waitcnt vmcnt(10)
	v_pk_fma_f32 v[64:65], v[64:65], v[142:143], v[242:243]
	v_pk_fma_f32 v[62:63], v[62:63], v[140:141], v[240:241]
	global_store_dwordx4 v157, v[62:65], s[76:77] nt
	global_load_dwordx4 v[240:243], v157, s[74:75] offset:512 nt
	s_waitcnt vmcnt(10)
	v_pk_fma_f32 v[60:61], v[60:61], v[146:147], v[246:247]
	v_pk_fma_f32 v[58:59], v[58:59], v[144:145], v[244:245]
	global_store_dwordx4 v157, v[58:61], s[76:77] offset:64 nt
	global_load_dwordx4 v[244:247], v157, s[74:75] offset:576 nt
	s_waitcnt vmcnt(10)
	v_pk_fma_f32 v[56:57], v[56:57], v[150:151], v[226:227]
	v_pk_fma_f32 v[54:55], v[54:55], v[148:149], v[224:225]
	global_store_dwordx4 v157, v[54:57], s[76:77] offset:512 nt
	s_add_u32 s74, s74, 0x20000
	s_addc_u32 s75, s75, 0
	global_load_dwordx4 v[224:227], v157, s[74:75] nt
	s_waitcnt vmcnt(10)
	v_pk_fma_f32 v[52:53], v[52:53], v[170:171], v[230:231]
	v_pk_fma_f32 v[50:51], v[50:51], v[168:169], v[228:229]
	global_store_dwordx4 v157, v[50:53], s[76:77] offset:576 nt
	global_load_dwordx4 v[228:231], v157, s[74:75] offset:64 nt
	s_add_u32 s76, s76, 0x20000
	s_addc_u32 s77, s77, 0
	s_waitcnt vmcnt(10)
	v_pk_fma_f32 v[48:49], v[48:49], v[142:143], v[234:235]
	v_pk_fma_f32 v[46:47], v[46:47], v[140:141], v[232:233]
	global_store_dwordx4 v157, v[46:49], s[76:77] nt
	global_load_dwordx4 v[232:235], v157, s[74:75] offset:512 nt
	s_waitcnt vmcnt(10)
	v_pk_fma_f32 v[44:45], v[44:45], v[146:147], v[238:239]
	v_pk_fma_f32 v[42:43], v[42:43], v[144:145], v[236:237]
	global_store_dwordx4 v157, v[42:45], s[76:77] offset:64 nt
	global_load_dwordx4 v[236:239], v157, s[74:75] offset:576 nt
	s_waitcnt vmcnt(10)
	v_pk_fma_f32 v[40:41], v[40:41], v[150:151], v[242:243]
	v_pk_fma_f32 v[38:39], v[38:39], v[148:149], v[240:241]
	global_store_dwordx4 v157, v[38:41], s[76:77] offset:512 nt
	s_add_u32 s74, s74, 0x20000
	s_addc_u32 s75, s75, 0
	global_load_dwordx4 v[240:243], v157, s[74:75] nt
	s_waitcnt vmcnt(10)
	v_pk_fma_f32 v[36:37], v[36:37], v[170:171], v[246:247]
	v_pk_fma_f32 v[34:35], v[34:35], v[168:169], v[244:245]
	global_store_dwordx4 v157, v[34:37], s[76:77] offset:576 nt
	global_load_dwordx4 v[244:247], v157, s[74:75] offset:64 nt
	s_add_u32 s76, s76, 0x20000
	s_addc_u32 s77, s77, 0
	s_waitcnt vmcnt(10)
	v_pk_fma_f32 v[32:33], v[32:33], v[142:143], v[226:227]
	v_pk_fma_f32 v[30:31], v[30:31], v[140:141], v[224:225]
	global_store_dwordx4 v157, v[30:33], s[76:77] nt
	global_load_dwordx4 v[224:227], v157, s[74:75] offset:512 nt
	s_waitcnt vmcnt(10)
	v_pk_fma_f32 v[28:29], v[28:29], v[146:147], v[230:231]
	v_pk_fma_f32 v[26:27], v[26:27], v[144:145], v[228:229]
	global_store_dwordx4 v157, v[26:29], s[76:77] offset:64 nt
	global_load_dwordx4 v[228:231], v157, s[74:75] offset:576 nt
	s_waitcnt vmcnt(10)
	v_pk_fma_f32 v[24:25], v[24:25], v[150:151], v[234:235]
	v_pk_fma_f32 v[22:23], v[22:23], v[148:149], v[232:233]
	global_store_dwordx4 v157, v[22:25], s[76:77] offset:512 nt
	s_waitcnt vmcnt(9)
	v_pk_fma_f32 v[20:21], v[20:21], v[170:171], v[238:239]
	v_pk_fma_f32 v[18:19], v[18:19], v[168:169], v[236:237]
	global_store_dwordx4 v157, v[18:21], s[76:77] offset:576 nt
	s_add_u32 s76, s76, 0x20000
	s_addc_u32 s77, s77, 0
	s_waitcnt vmcnt(8)
	v_pk_fma_f32 v[16:17], v[16:17], v[142:143], v[242:243]
	v_pk_fma_f32 v[14:15], v[14:15], v[140:141], v[240:241]
	global_store_dwordx4 v157, v[14:17], s[76:77] nt
	s_waitcnt vmcnt(7)
	v_pk_fma_f32 v[12:13], v[12:13], v[146:147], v[246:247]
	v_pk_fma_f32 v[10:11], v[10:11], v[144:145], v[244:245]
	global_store_dwordx4 v157, v[10:13], s[76:77] offset:64 nt
	s_waitcnt vmcnt(6)
	v_pk_fma_f32 v[8:9], v[8:9], v[150:151], v[226:227]
	v_pk_fma_f32 v[6:7], v[6:7], v[148:149], v[224:225]
	global_store_dwordx4 v157, v[6:9], s[76:77] offset:512 nt
	s_waitcnt vmcnt(5)
	v_pk_fma_f32 v[4:5], v[4:5], v[170:171], v[230:231]
	v_pk_fma_f32 v[2:3], v[2:3], v[168:169], v[228:229]
	global_store_dwordx4 v157, v[2:5], s[76:77] offset:576 nt
	s_branch .LBB0_24

.LBB0_234:
	s_add_u32 s39, s46, 0xfff80080
	s_addc_u32 s48, s47, -1
	s_add_i32 s62, 0, 0x10000
	v_add_u32_e32 v156, s62, v141
	ds_read_b128 v[144:147], v156
	ds_read_b128 v[148:151], v156 offset:1024
	ds_read_b128 v[152:155], v156 offset:2048
	ds_read_b128 v[168:171], v156 offset:3072
	s_cmp_eq_u32 s13, 28
	s_cselect_b32 s51, s43, s48
	s_cselect_b32 s50, s42, s39
	s_cselect_b32 s49, s45, s12
	s_cselect_b32 s48, s44, s1
	s_add_i32 m0, s53, 0xc000
	ds_read_b128 v[172:175], v143
	ds_read_b128 v[176:179], v143 offset:1024
	ds_read_b128 v[180:183], v143 offset:2048
	ds_read_b128 v[184:187], v143 offset:3072
	ds_read_b128 v[188:191], v143 offset:4096
	ds_read_b128 v[192:195], v143 offset:5120
	ds_read_b128 v[196:199], v143 offset:6144
	ds_read_b128 v[224:227], v143 offset:7168
	global_load_lds_dwordx4 v136, s[46:47]
	s_add_i32 m0, s53, 0xe000
	s_nop 0
	global_load_lds_dwordx4 v138, s[46:47]
	s_waitcnt lgkmcnt(8)
	s_barrier
	s_waitcnt lgkmcnt(0)
	v_mfma_f32_16x16x32_bf16 v[126:129], v[144:147], v[172:175], v[126:129]
	v_mfma_f32_16x16x32_bf16 v[122:125], v[152:155], v[172:175], v[122:125]
	v_mfma_f32_16x16x32_bf16 v[118:121], v[144:147], v[180:183], v[118:121]
	v_mfma_f32_16x16x32_bf16 v[114:117], v[152:155], v[180:183], v[114:117]
	v_mfma_f32_16x16x32_bf16 v[102:105], v[144:147], v[188:191], v[102:105]
	v_mfma_f32_16x16x32_bf16 v[98:101], v[152:155], v[188:191], v[98:101]
	v_mfma_f32_16x16x32_bf16 v[86:89], v[144:147], v[196:199], v[86:89]
	v_mfma_f32_16x16x32_bf16 v[82:85], v[152:155], v[196:199], v[82:85]
	v_mfma_f32_16x16x32_bf16 v[126:129], v[148:151], v[176:179], v[126:129]
	v_mfma_f32_16x16x32_bf16 v[122:125], v[168:171], v[176:179], v[122:125]
	v_mfma_f32_16x16x32_bf16 v[118:121], v[148:151], v[184:187], v[118:121]
	v_mfma_f32_16x16x32_bf16 v[114:117], v[168:171], v[184:187], v[114:117]
	v_mfma_f32_16x16x32_bf16 v[102:105], v[148:151], v[192:195], v[102:105]
	v_mfma_f32_16x16x32_bf16 v[98:101], v[168:171], v[192:195], v[98:101]
	v_mfma_f32_16x16x32_bf16 v[86:89], v[148:151], v[224:227], v[86:89]
	v_mfma_f32_16x16x32_bf16 v[82:85], v[168:171], v[224:227], v[82:85]
	s_barrier
	s_add_i32 s39, 0, 0x14000
	v_add_u32_e32 v156, s39, v141
	s_add_i32 s62, s62, s52
	ds_read_b128 v[228:231], v156
	ds_read_b128 v[232:235], v156 offset:1024
	ds_read_b128 v[236:239], v156 offset:2048
	ds_read_b128 v[240:243], v156 offset:3072
	s_add_u32 s76, s48, s94
	s_addc_u32 s77, s49, s95
	s_mov_b32 m0, s62
	s_nop 0
	global_load_lds_dwordx4 v0, s[48:49]
	s_add_i32 m0, s62, 0x2000
	s_nop 0
	global_load_lds_dwordx4 v130, s[48:49]
	s_mov_b32 m0, s53
	s_add_u32 s78, s50, s94
	s_addc_u32 s79, s51, s95
	s_barrier
	s_waitcnt lgkmcnt(0)
	v_mfma_f32_16x16x32_bf16 v[110:113], v[228:231], v[172:175], v[110:113]
	v_mfma_f32_16x16x32_bf16 v[106:109], v[236:239], v[172:175], v[106:109]
	v_mfma_f32_16x16x32_bf16 v[94:97], v[228:231], v[180:183], v[94:97]
	v_mfma_f32_16x16x32_bf16 v[90:93], v[236:239], v[180:183], v[90:93]
	v_mfma_f32_16x16x32_bf16 v[78:81], v[228:231], v[188:191], v[78:81]
	v_mfma_f32_16x16x32_bf16 v[74:77], v[236:239], v[188:191], v[74:77]
	v_mfma_f32_16x16x32_bf16 v[70:73], v[228:231], v[196:199], v[70:73]
	v_mfma_f32_16x16x32_bf16 v[66:69], v[236:239], v[196:199], v[66:69]
	v_mfma_f32_16x16x32_bf16 v[110:113], v[232:235], v[176:179], v[110:113]
	v_mfma_f32_16x16x32_bf16 v[106:109], v[240:243], v[176:179], v[106:109]
	v_mfma_f32_16x16x32_bf16 v[94:97], v[232:235], v[184:187], v[94:97]
	v_mfma_f32_16x16x32_bf16 v[90:93], v[240:243], v[184:187], v[90:93]
	v_mfma_f32_16x16x32_bf16 v[78:81], v[232:235], v[192:195], v[78:81]
	v_mfma_f32_16x16x32_bf16 v[74:77], v[240:243], v[192:195], v[74:77]
	v_mfma_f32_16x16x32_bf16 v[70:73], v[232:235], v[224:227], v[70:73]
	v_mfma_f32_16x16x32_bf16 v[66:69], v[240:243], v[224:227], v[66:69]
	s_barrier
	ds_read_b128 v[172:175], v143 offset:16384
	ds_read_b128 v[176:179], v143 offset:17408
	ds_read_b128 v[180:183], v143 offset:18432
	ds_read_b128 v[184:187], v143 offset:19456
	ds_read_b128 v[188:191], v143 offset:20480
	ds_read_b128 v[192:195], v143 offset:21504
	ds_read_b128 v[196:199], v143 offset:22528
	ds_read_b128 v[224:227], v143 offset:23552
	global_load_lds_dwordx4 v134, s[50:51]
	s_mov_b32 m0, s54
	s_nop 0
	global_load_lds_dwordx4 v132, s[50:51]
	s_barrier
	s_waitcnt lgkmcnt(0)
	v_mfma_f32_16x16x32_bf16 v[62:65], v[144:147], v[172:175], v[62:65]
	v_mfma_f32_16x16x32_bf16 v[58:61], v[152:155], v[172:175], v[58:61]
	v_mfma_f32_16x16x32_bf16 v[54:57], v[144:147], v[180:183], v[54:57]
	v_mfma_f32_16x16x32_bf16 v[50:53], v[152:155], v[180:183], v[50:53]
	v_mfma_f32_16x16x32_bf16 v[38:41], v[144:147], v[188:191], v[38:41]
	v_mfma_f32_16x16x32_bf16 v[34:37], v[152:155], v[188:191], v[34:37]
	v_mfma_f32_16x16x32_bf16 v[22:25], v[144:147], v[196:199], v[22:25]
	v_mfma_f32_16x16x32_bf16 v[18:21], v[152:155], v[196:199], v[18:21]
	v_mfma_f32_16x16x32_bf16 v[62:65], v[148:151], v[176:179], v[62:65]
	v_mfma_f32_16x16x32_bf16 v[58:61], v[168:171], v[176:179], v[58:61]
	v_mfma_f32_16x16x32_bf16 v[54:57], v[148:151], v[184:187], v[54:57]
	v_mfma_f32_16x16x32_bf16 v[50:53], v[168:171], v[184:187], v[50:53]
	v_mfma_f32_16x16x32_bf16 v[38:41], v[148:151], v[192:195], v[38:41]
	v_mfma_f32_16x16x32_bf16 v[34:37], v[168:171], v[192:195], v[34:37]
	v_mfma_f32_16x16x32_bf16 v[22:25], v[148:151], v[224:227], v[22:25]
	v_mfma_f32_16x16x32_bf16 v[18:21], v[168:171], v[224:227], v[18:21]
	s_barrier
	s_add_u32 s62, s48, 0x80000
	s_addc_u32 s63, s49, 0
	s_add_i32 s39, s39, s52
	s_mov_b32 m0, s39
	s_nop 0
	global_load_lds_dwordx4 v0, s[62:63]
	s_add_i32 m0, s39, 0x2000
	s_nop 0
	global_load_lds_dwordx4 v130, s[62:63]
	s_add_i32 s39, 0, 0x18000
	v_add_u32_e32 v161, s39, v141
	s_waitcnt vmcnt(6)
	s_barrier
	v_mfma_f32_16x16x32_bf16 v[46:49], v[228:231], v[172:175], v[46:49]
	v_mfma_f32_16x16x32_bf16 v[42:45], v[236:239], v[172:175], v[42:45]
	v_mfma_f32_16x16x32_bf16 v[30:33], v[228:231], v[180:183], v[30:33]
	v_mfma_f32_16x16x32_bf16 v[26:29], v[236:239], v[180:183], v[26:29]
	v_mfma_f32_16x16x32_bf16 v[14:17], v[228:231], v[188:191], v[14:17]
	v_mfma_f32_16x16x32_bf16 v[10:13], v[236:239], v[188:191], v[10:13]
	v_mfma_f32_16x16x32_bf16 v[6:9], v[228:231], v[196:199], v[6:9]
	v_mfma_f32_16x16x32_bf16 v[2:5], v[236:239], v[196:199], v[2:5]
	v_mfma_f32_16x16x32_bf16 v[46:49], v[232:235], v[176:179], v[46:49]
	v_mfma_f32_16x16x32_bf16 v[42:45], v[240:243], v[176:179], v[42:45]
	v_mfma_f32_16x16x32_bf16 v[30:33], v[232:235], v[184:187], v[30:33]
	v_mfma_f32_16x16x32_bf16 v[26:29], v[240:243], v[184:187], v[26:29]
	v_mfma_f32_16x16x32_bf16 v[14:17], v[232:235], v[192:195], v[14:17]
	v_mfma_f32_16x16x32_bf16 v[10:13], v[240:243], v[192:195], v[10:13]
	v_mfma_f32_16x16x32_bf16 v[6:9], v[232:235], v[224:227], v[6:9]
	v_mfma_f32_16x16x32_bf16 v[2:5], v[240:243], v[224:227], v[2:5]
	s_barrier
	ds_read_b128 v[144:147], v161
	ds_read_b128 v[148:151], v161 offset:1024
	ds_read_b128 v[152:155], v161 offset:2048
	ds_read_b128 v[168:171], v161 offset:3072
	s_add_u32 s50, s50, 0x80000
	s_addc_u32 s51, s51, 0
	s_mov_b32 m0, s55
	ds_read_b128 v[172:175], v143 offset:32768
	ds_read_b128 v[176:179], v143 offset:33792
	ds_read_b128 v[180:183], v143 offset:34816
	ds_read_b128 v[184:187], v143 offset:35840
	ds_read_b128 v[188:191], v143 offset:36864
	ds_read_b128 v[192:195], v143 offset:37888
	ds_read_b128 v[196:199], v143 offset:38912
	ds_read_b128 v[224:227], v143 offset:39936
	global_load_lds_dwordx4 v134, s[50:51]
	s_mov_b32 m0, s56
	s_nop 0
	global_load_lds_dwordx4 v132, s[50:51]
	s_waitcnt lgkmcnt(8)
	s_barrier
	s_waitcnt lgkmcnt(0)
	v_mfma_f32_16x16x32_bf16 v[126:129], v[144:147], v[172:175], v[126:129]
	v_mfma_f32_16x16x32_bf16 v[122:125], v[152:155], v[172:175], v[122:125]
	v_mfma_f32_16x16x32_bf16 v[118:121], v[144:147], v[180:183], v[118:121]
	v_mfma_f32_16x16x32_bf16 v[114:117], v[152:155], v[180:183], v[114:117]
	v_mfma_f32_16x16x32_bf16 v[102:105], v[144:147], v[188:191], v[102:105]
	v_mfma_f32_16x16x32_bf16 v[98:101], v[152:155], v[188:191], v[98:101]
	v_mfma_f32_16x16x32_bf16 v[86:89], v[144:147], v[196:199], v[86:89]
	v_mfma_f32_16x16x32_bf16 v[82:85], v[152:155], v[196:199], v[82:85]
	v_mfma_f32_16x16x32_bf16 v[126:129], v[148:151], v[176:179], v[126:129]
	v_mfma_f32_16x16x32_bf16 v[122:125], v[168:171], v[176:179], v[122:125]
	v_mfma_f32_16x16x32_bf16 v[118:121], v[148:151], v[184:187], v[118:121]
	v_mfma_f32_16x16x32_bf16 v[114:117], v[168:171], v[184:187], v[114:117]
	v_mfma_f32_16x16x32_bf16 v[102:105], v[148:151], v[192:195], v[102:105]
	v_mfma_f32_16x16x32_bf16 v[98:101], v[168:171], v[192:195], v[98:101]
	v_mfma_f32_16x16x32_bf16 v[86:89], v[148:151], v[224:227], v[86:89]
	v_mfma_f32_16x16x32_bf16 v[82:85], v[168:171], v[224:227], v[82:85]
	s_barrier
	s_add_i32 s50, 0, 0x1c000
	s_add_i32 s39, s39, s52
	v_add_u32_e32 v161, s50, v141
	s_mov_b32 m0, s39
	ds_read_b128 v[228:231], v161
	ds_read_b128 v[232:235], v161 offset:1024
	ds_read_b128 v[236:239], v161 offset:2048
	ds_read_b128 v[240:243], v161 offset:3072
	global_load_lds_dwordx4 v0, s[76:77]
	s_add_i32 m0, s39, 0x2000
	s_nop 0
	global_load_lds_dwordx4 v130, s[76:77]
	s_mov_b32 m0, s57
	s_barrier
	s_waitcnt lgkmcnt(0)
	v_mfma_f32_16x16x32_bf16 v[110:113], v[228:231], v[172:175], v[110:113]
	v_mfma_f32_16x16x32_bf16 v[106:109], v[236:239], v[172:175], v[106:109]
	v_mfma_f32_16x16x32_bf16 v[94:97], v[228:231], v[180:183], v[94:97]
	v_mfma_f32_16x16x32_bf16 v[90:93], v[236:239], v[180:183], v[90:93]
	v_mfma_f32_16x16x32_bf16 v[78:81], v[228:231], v[188:191], v[78:81]
	v_mfma_f32_16x16x32_bf16 v[74:77], v[236:239], v[188:191], v[74:77]
	v_mfma_f32_16x16x32_bf16 v[70:73], v[228:231], v[196:199], v[70:73]
	v_mfma_f32_16x16x32_bf16 v[66:69], v[236:239], v[196:199], v[66:69]
	v_mfma_f32_16x16x32_bf16 v[110:113], v[232:235], v[176:179], v[110:113]
	v_mfma_f32_16x16x32_bf16 v[106:109], v[240:243], v[176:179], v[106:109]
	v_mfma_f32_16x16x32_bf16 v[94:97], v[232:235], v[184:187], v[94:97]
	v_mfma_f32_16x16x32_bf16 v[90:93], v[240:243], v[184:187], v[90:93]
	v_mfma_f32_16x16x32_bf16 v[78:81], v[232:235], v[192:195], v[78:81]
	v_mfma_f32_16x16x32_bf16 v[74:77], v[240:243], v[192:195], v[74:77]
	v_mfma_f32_16x16x32_bf16 v[70:73], v[232:235], v[224:227], v[70:73]
	v_mfma_f32_16x16x32_bf16 v[66:69], v[240:243], v[224:227], v[66:69]
	s_barrier
	ds_read_b128 v[172:175], v143 offset:49152
	ds_read_b128 v[176:179], v143 offset:50176
	ds_read_b128 v[180:183], v143 offset:51200
	ds_read_b128 v[184:187], v143 offset:52224
	ds_read_b128 v[188:191], v143 offset:53248
	ds_read_b128 v[192:195], v143 offset:54272
	ds_read_b128 v[196:199], v143 offset:55296
	ds_read_b128 v[224:227], v143 offset:56320
	global_load_lds_dwordx4 v134, s[78:79]
	s_mov_b32 m0, s58
	s_nop 0
	global_load_lds_dwordx4 v132, s[78:79]
	s_barrier
	s_waitcnt lgkmcnt(0)
	v_mfma_f32_16x16x32_bf16 v[62:65], v[144:147], v[172:175], v[62:65]
	v_mfma_f32_16x16x32_bf16 v[58:61], v[152:155], v[172:175], v[58:61]
	v_mfma_f32_16x16x32_bf16 v[54:57], v[144:147], v[180:183], v[54:57]
	v_mfma_f32_16x16x32_bf16 v[50:53], v[152:155], v[180:183], v[50:53]
	v_mfma_f32_16x16x32_bf16 v[38:41], v[144:147], v[188:191], v[38:41]
	v_mfma_f32_16x16x32_bf16 v[34:37], v[152:155], v[188:191], v[34:37]
	v_mfma_f32_16x16x32_bf16 v[22:25], v[144:147], v[196:199], v[22:25]
	v_mfma_f32_16x16x32_bf16 v[18:21], v[152:155], v[196:199], v[18:21]
	v_mfma_f32_16x16x32_bf16 v[62:65], v[148:151], v[176:179], v[62:65]
	v_mfma_f32_16x16x32_bf16 v[58:61], v[168:171], v[176:179], v[58:61]
	v_mfma_f32_16x16x32_bf16 v[54:57], v[148:151], v[184:187], v[54:57]
	v_mfma_f32_16x16x32_bf16 v[50:53], v[168:171], v[184:187], v[50:53]
	v_mfma_f32_16x16x32_bf16 v[38:41], v[148:151], v[192:195], v[38:41]
	v_mfma_f32_16x16x32_bf16 v[34:37], v[168:171], v[192:195], v[34:37]
	v_mfma_f32_16x16x32_bf16 v[22:25], v[148:151], v[224:227], v[22:25]
	v_mfma_f32_16x16x32_bf16 v[18:21], v[168:171], v[224:227], v[18:21]
	s_barrier
	s_add_u32 s48, s48, 0x80080
	s_addc_u32 s49, s49, 0
	s_add_i32 s39, s50, s52
	s_mov_b32 m0, s39
	s_nop 0
	global_load_lds_dwordx4 v0, s[48:49]
	s_add_i32 m0, s39, 0x2000
	s_nop 0
	global_load_lds_dwordx4 v130, s[48:49]
	s_add_i32 s13, s13, 2
	s_add_u32 s46, s46, 0x100
	s_addc_u32 s47, s47, 0
	s_add_u32 s1, s1, 0x100
	s_addc_u32 s12, s12, 0
	s_waitcnt vmcnt(6)
	s_barrier
	v_mfma_f32_16x16x32_bf16 v[46:49], v[228:231], v[172:175], v[46:49]
	v_mfma_f32_16x16x32_bf16 v[42:45], v[236:239], v[172:175], v[42:45]
	v_mfma_f32_16x16x32_bf16 v[30:33], v[228:231], v[180:183], v[30:33]
	v_mfma_f32_16x16x32_bf16 v[26:29], v[236:239], v[180:183], v[26:29]
	v_mfma_f32_16x16x32_bf16 v[14:17], v[228:231], v[188:191], v[14:17]
	v_mfma_f32_16x16x32_bf16 v[10:13], v[236:239], v[188:191], v[10:13]
	v_mfma_f32_16x16x32_bf16 v[6:9], v[228:231], v[196:199], v[6:9]
	v_mfma_f32_16x16x32_bf16 v[2:5], v[236:239], v[196:199], v[2:5]
	v_mfma_f32_16x16x32_bf16 v[46:49], v[232:235], v[176:179], v[46:49]
	v_mfma_f32_16x16x32_bf16 v[42:45], v[240:243], v[176:179], v[42:45]
	v_mfma_f32_16x16x32_bf16 v[30:33], v[232:235], v[184:187], v[30:33]
	v_mfma_f32_16x16x32_bf16 v[26:29], v[240:243], v[184:187], v[26:29]
	v_mfma_f32_16x16x32_bf16 v[14:17], v[232:235], v[192:195], v[14:17]
	v_mfma_f32_16x16x32_bf16 v[10:13], v[240:243], v[192:195], v[10:13]
	v_mfma_f32_16x16x32_bf16 v[6:9], v[232:235], v[224:227], v[6:9]
	v_mfma_f32_16x16x32_bf16 v[2:5], v[240:243], v[224:227], v[2:5]
	s_barrier
	s_cmp_gt_u32 s13, 29
	s_cbranch_scc0 .LBB0_234
	v_readlane_b32 s6, v255, 23
	v_lshl_add_u32 v150, s61, 8, v140
	v_lshl_or_b32 v144, s60, 8, v142
	v_readlane_b32 s7, v255, 24
	v_ashrrev_i32_e32 v145, 31, v144
	s_movk_i32 s1, 0x5800
	v_mov_b64_e32 v[146:147], s[6:7]
	v_cvt_pk_bf16_f32 v70, v70, v71
	v_cvt_pk_bf16_f32 v71, v72, v73
	v_cvt_pk_bf16_f32 v72, v66, v67
	v_add_u32_e32 v66, 0x80, v150
	v_mad_i64_i32 v[148:149], s[12:13], v150, s1, v[146:147]
	v_lshlrev_b64 v[144:145], 1, v[144:145]
	v_cvt_pk_bf16_f32 v110, v110, v111
	v_cvt_pk_bf16_f32 v111, v112, v113
	v_cvt_pk_bf16_f32 v112, v106, v107
	v_or_b32_e32 v106, 16, v150
	v_mad_i64_i32 v[66:67], s[12:13], v66, s1, v[146:147]
	v_cvt_pk_bf16_f32 v46, v46, v47
	v_cvt_pk_bf16_f32 v47, v48, v49
	v_cvt_pk_bf16_f32 v48, v42, v43
	v_add_u32_e32 v42, 0x90, v150
	v_lshl_add_u64 v[148:149], v[148:149], 0, v[144:145]
	v_cvt_pk_bf16_f32 v113, v108, v109
	v_mad_i64_i32 v[106:107], s[12:13], v106, s1, v[146:147]
	v_cvt_pk_bf16_f32 v94, v94, v95
	v_cvt_pk_bf16_f32 v95, v96, v97
	v_cvt_pk_bf16_f32 v96, v90, v91
	v_or_b32_e32 v90, 32, v150
	v_lshl_add_u64 v[66:67], v[66:67], 0, v[144:145]
	v_cvt_pk_bf16_f32 v49, v44, v45
	v_mad_i64_i32 v[42:43], s[12:13], v42, s1, v[146:147]
	v_cvt_pk_bf16_f32 v30, v30, v31
	v_cvt_pk_bf16_f32 v31, v32, v33
	v_cvt_pk_bf16_f32 v32, v26, v27
	v_add_u32_e32 v26, 0xa0, v150
	global_store_dwordx4 v[148:149], v[110:113], off offset:256
	v_cvt_pk_bf16_f32 v97, v92, v93
	v_mad_i64_i32 v[90:91], s[12:13], v90, s1, v[146:147]
	v_lshl_add_u64 v[110:111], v[106:107], 0, v[144:145]
	v_cvt_pk_bf16_f32 v78, v78, v79
	v_cvt_pk_bf16_f32 v79, v80, v81
	v_cvt_pk_bf16_f32 v80, v74, v75
	v_or_b32_e32 v74, 48, v150
	global_store_dwordx4 v[66:67], v[46:49], off offset:256
	v_cvt_pk_bf16_f32 v33, v28, v29
	v_mad_i64_i32 v[26:27], s[12:13], v26, s1, v[146:147]
	v_lshl_add_u64 v[46:47], v[42:43], 0, v[144:145]
	v_cvt_pk_bf16_f32 v14, v14, v15
	v_cvt_pk_bf16_f32 v15, v16, v17
	v_cvt_pk_bf16_f32 v16, v10, v11
	v_add_u32_e32 v10, 0xb0, v150
	global_store_dwordx4 v[110:111], v[94:97], off offset:256
	v_cvt_pk_bf16_f32 v81, v76, v77
	v_mad_i64_i32 v[74:75], s[12:13], v74, s1, v[146:147]
	v_lshl_add_u64 v[94:95], v[90:91], 0, v[144:145]
	global_store_dwordx4 v[46:47], v[30:33], off offset:256
	v_cvt_pk_bf16_f32 v17, v12, v13
	v_mad_i64_i32 v[10:11], s[12:13], v10, s1, v[146:147]
	v_lshl_add_u64 v[30:31], v[26:27], 0, v[144:145]
	v_cvt_pk_bf16_f32 v126, v126, v127
	v_cvt_pk_bf16_f32 v127, v128, v129
	v_cvt_pk_bf16_f32 v128, v122, v123
	v_cvt_pk_bf16_f32 v129, v124, v125
	v_cvt_pk_bf16_f32 v106, v118, v119
	v_cvt_pk_bf16_f32 v107, v120, v121
	v_cvt_pk_bf16_f32 v108, v114, v115
	v_cvt_pk_bf16_f32 v109, v116, v117
	v_cvt_pk_bf16_f32 v90, v102, v103
	v_cvt_pk_bf16_f32 v91, v104, v105
	v_cvt_pk_bf16_f32 v92, v98, v99
	v_cvt_pk_bf16_f32 v93, v100, v101
	global_store_dwordx4 v[94:95], v[78:81], off offset:256
	v_cvt_pk_bf16_f32 v76, v82, v83
	v_cvt_pk_bf16_f32 v77, v84, v85
	v_lshl_add_u64 v[78:79], v[74:75], 0, v[144:145]
	v_cvt_pk_bf16_f32 v74, v86, v87
	v_cvt_pk_bf16_f32 v75, v88, v89
	v_cvt_pk_bf16_f32 v73, v68, v69
	v_cvt_pk_bf16_f32 v62, v62, v63
	v_cvt_pk_bf16_f32 v63, v64, v65
	v_cvt_pk_bf16_f32 v64, v58, v59
	v_cvt_pk_bf16_f32 v65, v60, v61
	v_cvt_pk_bf16_f32 v42, v54, v55
	v_cvt_pk_bf16_f32 v43, v56, v57
	v_cvt_pk_bf16_f32 v44, v50, v51
	v_cvt_pk_bf16_f32 v45, v52, v53
	v_cvt_pk_bf16_f32 v26, v38, v39
	v_cvt_pk_bf16_f32 v27, v40, v41
	v_cvt_pk_bf16_f32 v28, v34, v35
	v_cvt_pk_bf16_f32 v29, v36, v37
	global_store_dwordx4 v[30:31], v[14:17], off offset:256
	v_cvt_pk_bf16_f32 v12, v18, v19
	v_cvt_pk_bf16_f32 v13, v20, v21
	v_lshl_add_u64 v[14:15], v[10:11], 0, v[144:145]
	v_cvt_pk_bf16_f32 v10, v22, v23
	v_cvt_pk_bf16_f32 v11, v24, v25
	v_cvt_pk_bf16_f32 v6, v6, v7
	v_cvt_pk_bf16_f32 v7, v8, v9
	v_cvt_pk_bf16_f32 v8, v2, v3
	v_cvt_pk_bf16_f32 v9, v4, v5
	s_and_b64 vcc, exec, s[40:41]
	s_mov_b32 s60, s0
	s_mov_b32 s61, s38
	s_mov_b64 s[48:49], s[44:45]
	s_mov_b64 s[46:47], s[42:43]
	global_store_dwordx4 v[148:149], v[126:129], off
	global_store_dwordx4 v[110:111], v[106:109], off
	global_store_dwordx4 v[94:95], v[90:93], off
	global_store_dwordx4 v[78:79], v[74:77], off
	global_store_dwordx4 v[78:79], v[70:73], off offset:256
	global_store_dwordx4 v[66:67], v[62:65], off
	global_store_dwordx4 v[46:47], v[42:45], off
	global_store_dwordx4 v[30:31], v[26:29], off
	global_store_dwordx4 v[14:15], v[10:13], off
	global_store_dwordx4 v[14:15], v[6:9], off offset:256
	s_cbranch_vccz .LBB0_227
	s_waitcnt vmcnt(0)
	v_readlane_b32 s60, v255, 21
	s_cmpk_gt_u32 s36, 0xff
	s_mov_b32 s18, s60
	v_readlane_b32 s61, v255, 22
	s_cbranch_scc1 .LBB0_238
	s_barrier

.LBB0_282:
	s_add_i32 s67, s50, 2
	s_add_u32 s51, s0, 0xfff80080
	s_addc_u32 s52, s1, -1
	s_add_i32 s68, 0, 0x10000
	v_add_u32_e32 v148, s68, v153
	ds_read_b128 v[136:139], v148
	ds_read_b128 v[140:143], v148 offset:1024
	ds_read_b128 v[144:147], v148 offset:2048
	ds_read_b128 v[148:151], v148 offset:3072
	s_cmp_eq_u32 s12, s50
	s_cselect_b32 s50, s48, s13
	s_cselect_b32 s53, s47, s52
	s_cselect_b32 s52, s46, s51
	s_cselect_b32 s51, s49, s66
	s_add_i32 m0, s55, 0xc000
	ds_read_b128 v[168:171], v155
	ds_read_b128 v[172:175], v155 offset:1024
	ds_read_b128 v[176:179], v155 offset:2048
	ds_read_b128 v[180:183], v155 offset:3072
	ds_read_b128 v[184:187], v155 offset:4096
	ds_read_b128 v[188:191], v155 offset:5120
	ds_read_b128 v[192:195], v155 offset:6144
	ds_read_b128 v[196:199], v155 offset:7168
	global_load_lds_dwordx4 v132, s[0:1]
	s_add_i32 m0, s55, 0xe000
	s_nop 0
	global_load_lds_dwordx4 v134, s[0:1]
	s_waitcnt lgkmcnt(8)
	s_barrier
	s_waitcnt lgkmcnt(0)
	v_mfma_f32_16x16x32_bf16 v[126:129], v[136:139], v[168:171], v[126:129]
	v_mfma_f32_16x16x32_bf16 v[122:125], v[144:147], v[168:171], v[122:125]
	v_mfma_f32_16x16x32_bf16 v[110:113], v[136:139], v[176:179], v[110:113]
	v_mfma_f32_16x16x32_bf16 v[106:109], v[144:147], v[176:179], v[106:109]
	v_mfma_f32_16x16x32_bf16 v[94:97], v[136:139], v[184:187], v[94:97]
	v_mfma_f32_16x16x32_bf16 v[90:93], v[144:147], v[184:187], v[90:93]
	v_mfma_f32_16x16x32_bf16 v[78:81], v[136:139], v[192:195], v[78:81]
	v_mfma_f32_16x16x32_bf16 v[74:77], v[144:147], v[192:195], v[74:77]
	v_mfma_f32_16x16x32_bf16 v[126:129], v[140:143], v[172:175], v[126:129]
	v_mfma_f32_16x16x32_bf16 v[122:125], v[148:151], v[172:175], v[122:125]
	v_mfma_f32_16x16x32_bf16 v[110:113], v[140:143], v[180:183], v[110:113]
	v_mfma_f32_16x16x32_bf16 v[106:109], v[148:151], v[180:183], v[106:109]
	v_mfma_f32_16x16x32_bf16 v[94:97], v[140:143], v[188:191], v[94:97]
	v_mfma_f32_16x16x32_bf16 v[90:93], v[148:151], v[188:191], v[90:93]
	v_mfma_f32_16x16x32_bf16 v[78:81], v[140:143], v[196:199], v[78:81]
	v_mfma_f32_16x16x32_bf16 v[74:77], v[148:151], v[196:199], v[74:77]
	s_barrier
	s_add_i32 s70, 0, 0x14000
	v_add_u32_e32 v156, s70, v153
	s_add_i32 s68, s68, s54
	ds_read_b128 v[224:227], v156
	ds_read_b128 v[228:231], v156 offset:1024
	ds_read_b128 v[232:235], v156 offset:2048
	ds_read_b128 v[236:239], v156 offset:3072
	s_add_u32 s76, s50, s94
	s_addc_u32 s77, s51, s95
	s_mov_b32 m0, s68
	s_nop 0
	global_load_lds_dwordx4 v0, s[50:51]
	s_add_i32 m0, s68, 0x2000
	s_nop 0
	global_load_lds_dwordx4 v130, s[50:51]
	s_mov_b32 m0, s55
	s_add_u32 s78, s52, s94
	s_addc_u32 s79, s53, s95
	s_barrier
	s_waitcnt lgkmcnt(0)
	v_mfma_f32_16x16x32_bf16 v[118:121], v[224:227], v[168:171], v[118:121]
	v_mfma_f32_16x16x32_bf16 v[114:117], v[232:235], v[168:171], v[114:117]
	v_mfma_f32_16x16x32_bf16 v[102:105], v[224:227], v[176:179], v[102:105]
	v_mfma_f32_16x16x32_bf16 v[98:101], v[232:235], v[176:179], v[98:101]
	v_mfma_f32_16x16x32_bf16 v[86:89], v[224:227], v[184:187], v[86:89]
	v_mfma_f32_16x16x32_bf16 v[82:85], v[232:235], v[184:187], v[82:85]
	v_mfma_f32_16x16x32_bf16 v[70:73], v[224:227], v[192:195], v[70:73]
	v_mfma_f32_16x16x32_bf16 v[66:69], v[232:235], v[192:195], v[66:69]
	v_mfma_f32_16x16x32_bf16 v[118:121], v[228:231], v[172:175], v[118:121]
	v_mfma_f32_16x16x32_bf16 v[114:117], v[236:239], v[172:175], v[114:117]
	v_mfma_f32_16x16x32_bf16 v[102:105], v[228:231], v[180:183], v[102:105]
	v_mfma_f32_16x16x32_bf16 v[98:101], v[236:239], v[180:183], v[98:101]
	v_mfma_f32_16x16x32_bf16 v[86:89], v[228:231], v[188:191], v[86:89]
	v_mfma_f32_16x16x32_bf16 v[82:85], v[236:239], v[188:191], v[82:85]
	v_mfma_f32_16x16x32_bf16 v[70:73], v[228:231], v[196:199], v[70:73]
	v_mfma_f32_16x16x32_bf16 v[66:69], v[236:239], v[196:199], v[66:69]
	s_barrier
	ds_read_b128 v[168:171], v155 offset:16384
	ds_read_b128 v[172:175], v155 offset:17408
	ds_read_b128 v[176:179], v155 offset:18432
	ds_read_b128 v[180:183], v155 offset:19456
	ds_read_b128 v[184:187], v155 offset:20480
	ds_read_b128 v[188:191], v155 offset:21504
	ds_read_b128 v[192:195], v155 offset:22528
	ds_read_b128 v[196:199], v155 offset:23552
	global_load_lds_dwordx4 v0, s[52:53]
	s_mov_b32 m0, s56
	s_nop 0
	global_load_lds_dwordx4 v130, s[52:53]
	s_barrier
	s_waitcnt lgkmcnt(0)
	v_mfma_f32_16x16x32_bf16 v[62:65], v[136:139], v[168:171], v[62:65]
	v_mfma_f32_16x16x32_bf16 v[58:61], v[144:147], v[168:171], v[58:61]
	v_mfma_f32_16x16x32_bf16 v[46:49], v[136:139], v[176:179], v[46:49]
	v_mfma_f32_16x16x32_bf16 v[42:45], v[144:147], v[176:179], v[42:45]
	v_mfma_f32_16x16x32_bf16 v[30:33], v[136:139], v[184:187], v[30:33]
	v_mfma_f32_16x16x32_bf16 v[26:29], v[144:147], v[184:187], v[26:29]
	v_mfma_f32_16x16x32_bf16 v[14:17], v[136:139], v[192:195], v[14:17]
	v_mfma_f32_16x16x32_bf16 v[10:13], v[144:147], v[192:195], v[10:13]
	v_mfma_f32_16x16x32_bf16 v[62:65], v[140:143], v[172:175], v[62:65]
	v_mfma_f32_16x16x32_bf16 v[58:61], v[148:151], v[172:175], v[58:61]
	v_mfma_f32_16x16x32_bf16 v[46:49], v[140:143], v[180:183], v[46:49]
	v_mfma_f32_16x16x32_bf16 v[42:45], v[148:151], v[180:183], v[42:45]
	v_mfma_f32_16x16x32_bf16 v[30:33], v[140:143], v[188:191], v[30:33]
	v_mfma_f32_16x16x32_bf16 v[26:29], v[148:151], v[188:191], v[26:29]
	v_mfma_f32_16x16x32_bf16 v[14:17], v[140:143], v[196:199], v[14:17]
	v_mfma_f32_16x16x32_bf16 v[10:13], v[148:151], v[196:199], v[10:13]
	s_barrier
	s_add_u32 s68, s50, 0x80000
	s_addc_u32 s69, s51, 0
	s_add_i32 s70, s70, s54
	s_mov_b32 m0, s70
	s_nop 0
	global_load_lds_dwordx4 v0, s[68:69]
	s_add_i32 m0, s70, 0x2000
	s_nop 0
	global_load_lds_dwordx4 v130, s[68:69]
	s_add_i32 s68, 0, 0x18000
	v_add_u32_e32 v148, s68, v153
	s_waitcnt vmcnt(6)
	s_barrier
	v_mfma_f32_16x16x32_bf16 v[54:57], v[224:227], v[168:171], v[54:57]
	v_mfma_f32_16x16x32_bf16 v[50:53], v[232:235], v[168:171], v[50:53]
	v_mfma_f32_16x16x32_bf16 v[38:41], v[224:227], v[176:179], v[38:41]
	v_mfma_f32_16x16x32_bf16 v[34:37], v[232:235], v[176:179], v[34:37]
	v_mfma_f32_16x16x32_bf16 v[22:25], v[224:227], v[184:187], v[22:25]
	v_mfma_f32_16x16x32_bf16 v[18:21], v[232:235], v[184:187], v[18:21]
	v_mfma_f32_16x16x32_bf16 v[6:9], v[224:227], v[192:195], v[6:9]
	v_mfma_f32_16x16x32_bf16 v[2:5], v[232:235], v[192:195], v[2:5]
	v_mfma_f32_16x16x32_bf16 v[54:57], v[228:231], v[172:175], v[54:57]
	v_mfma_f32_16x16x32_bf16 v[50:53], v[236:239], v[172:175], v[50:53]
	v_mfma_f32_16x16x32_bf16 v[38:41], v[228:231], v[180:183], v[38:41]
	v_mfma_f32_16x16x32_bf16 v[34:37], v[236:239], v[180:183], v[34:37]
	v_mfma_f32_16x16x32_bf16 v[22:25], v[228:231], v[188:191], v[22:25]
	v_mfma_f32_16x16x32_bf16 v[18:21], v[236:239], v[188:191], v[18:21]
	v_mfma_f32_16x16x32_bf16 v[6:9], v[228:231], v[196:199], v[6:9]
	v_mfma_f32_16x16x32_bf16 v[2:5], v[236:239], v[196:199], v[2:5]
	s_barrier
	ds_read_b128 v[136:139], v148
	ds_read_b128 v[140:143], v148 offset:1024
	ds_read_b128 v[144:147], v148 offset:2048
	ds_read_b128 v[148:151], v148 offset:3072
	s_add_u32 s52, s52, 0x80000
	s_addc_u32 s53, s53, 0
	s_mov_b32 m0, s57
	ds_read_b128 v[168:171], v155 offset:32768
	ds_read_b128 v[172:175], v155 offset:33792
	ds_read_b128 v[176:179], v155 offset:34816
	ds_read_b128 v[180:183], v155 offset:35840
	ds_read_b128 v[184:187], v155 offset:36864
	ds_read_b128 v[188:191], v155 offset:37888
	ds_read_b128 v[192:195], v155 offset:38912
	ds_read_b128 v[196:199], v155 offset:39936
	global_load_lds_dwordx4 v0, s[52:53]
	s_mov_b32 m0, s58
	s_nop 0
	global_load_lds_dwordx4 v130, s[52:53]
	s_waitcnt lgkmcnt(8)
	s_barrier
	s_waitcnt lgkmcnt(0)
	v_mfma_f32_16x16x32_bf16 v[126:129], v[136:139], v[168:171], v[126:129]
	v_mfma_f32_16x16x32_bf16 v[122:125], v[144:147], v[168:171], v[122:125]
	v_mfma_f32_16x16x32_bf16 v[110:113], v[136:139], v[176:179], v[110:113]
	v_mfma_f32_16x16x32_bf16 v[106:109], v[144:147], v[176:179], v[106:109]
	v_mfma_f32_16x16x32_bf16 v[94:97], v[136:139], v[184:187], v[94:97]
	v_mfma_f32_16x16x32_bf16 v[90:93], v[144:147], v[184:187], v[90:93]
	v_mfma_f32_16x16x32_bf16 v[78:81], v[136:139], v[192:195], v[78:81]
	v_mfma_f32_16x16x32_bf16 v[74:77], v[144:147], v[192:195], v[74:77]
	v_mfma_f32_16x16x32_bf16 v[126:129], v[140:143], v[172:175], v[126:129]
	v_mfma_f32_16x16x32_bf16 v[122:125], v[148:151], v[172:175], v[122:125]
	v_mfma_f32_16x16x32_bf16 v[110:113], v[140:143], v[180:183], v[110:113]
	v_mfma_f32_16x16x32_bf16 v[106:109], v[148:151], v[180:183], v[106:109]
	v_mfma_f32_16x16x32_bf16 v[94:97], v[140:143], v[188:191], v[94:97]
	v_mfma_f32_16x16x32_bf16 v[90:93], v[148:151], v[188:191], v[90:93]
	v_mfma_f32_16x16x32_bf16 v[78:81], v[140:143], v[196:199], v[78:81]
	v_mfma_f32_16x16x32_bf16 v[74:77], v[148:151], v[196:199], v[74:77]
	s_barrier
	s_add_i32 s52, 0, 0x1c000
	s_add_i32 s53, s68, s54
	v_add_u32_e32 v161, s52, v153
	s_mov_b32 m0, s53
	ds_read_b128 v[224:227], v161
	ds_read_b128 v[228:231], v161 offset:1024
	ds_read_b128 v[232:235], v161 offset:2048
	ds_read_b128 v[236:239], v161 offset:3072
	global_load_lds_dwordx4 v0, s[76:77]
	s_add_i32 m0, s53, 0x2000
	s_nop 0
	global_load_lds_dwordx4 v130, s[76:77]
	s_mov_b32 m0, s59
	s_barrier
	s_waitcnt lgkmcnt(0)
	v_mfma_f32_16x16x32_bf16 v[118:121], v[224:227], v[168:171], v[118:121]
	v_mfma_f32_16x16x32_bf16 v[114:117], v[232:235], v[168:171], v[114:117]
	v_mfma_f32_16x16x32_bf16 v[102:105], v[224:227], v[176:179], v[102:105]
	v_mfma_f32_16x16x32_bf16 v[98:101], v[232:235], v[176:179], v[98:101]
	v_mfma_f32_16x16x32_bf16 v[86:89], v[224:227], v[184:187], v[86:89]
	v_mfma_f32_16x16x32_bf16 v[82:85], v[232:235], v[184:187], v[82:85]
	v_mfma_f32_16x16x32_bf16 v[70:73], v[224:227], v[192:195], v[70:73]
	v_mfma_f32_16x16x32_bf16 v[66:69], v[232:235], v[192:195], v[66:69]
	v_mfma_f32_16x16x32_bf16 v[118:121], v[228:231], v[172:175], v[118:121]
	v_mfma_f32_16x16x32_bf16 v[114:117], v[236:239], v[172:175], v[114:117]
	v_mfma_f32_16x16x32_bf16 v[102:105], v[228:231], v[180:183], v[102:105]
	v_mfma_f32_16x16x32_bf16 v[98:101], v[236:239], v[180:183], v[98:101]
	v_mfma_f32_16x16x32_bf16 v[86:89], v[228:231], v[188:191], v[86:89]
	v_mfma_f32_16x16x32_bf16 v[82:85], v[236:239], v[188:191], v[82:85]
	v_mfma_f32_16x16x32_bf16 v[70:73], v[228:231], v[196:199], v[70:73]
	v_mfma_f32_16x16x32_bf16 v[66:69], v[236:239], v[196:199], v[66:69]
	s_barrier
	ds_read_b128 v[168:171], v155 offset:49152
	ds_read_b128 v[172:175], v155 offset:50176
	ds_read_b128 v[176:179], v155 offset:51200
	ds_read_b128 v[180:183], v155 offset:52224
	ds_read_b128 v[184:187], v155 offset:53248
	ds_read_b128 v[188:191], v155 offset:54272
	ds_read_b128 v[192:195], v155 offset:55296
	ds_read_b128 v[196:199], v155 offset:56320
	global_load_lds_dwordx4 v0, s[78:79]
	s_mov_b32 m0, s60
	s_nop 0
	global_load_lds_dwordx4 v130, s[78:79]
	s_barrier
	s_waitcnt lgkmcnt(0)
	v_mfma_f32_16x16x32_bf16 v[62:65], v[136:139], v[168:171], v[62:65]
	v_mfma_f32_16x16x32_bf16 v[58:61], v[144:147], v[168:171], v[58:61]
	v_mfma_f32_16x16x32_bf16 v[46:49], v[136:139], v[176:179], v[46:49]
	v_mfma_f32_16x16x32_bf16 v[42:45], v[144:147], v[176:179], v[42:45]
	v_mfma_f32_16x16x32_bf16 v[30:33], v[136:139], v[184:187], v[30:33]
	v_mfma_f32_16x16x32_bf16 v[26:29], v[144:147], v[184:187], v[26:29]
	v_mfma_f32_16x16x32_bf16 v[14:17], v[136:139], v[192:195], v[14:17]
	v_mfma_f32_16x16x32_bf16 v[10:13], v[144:147], v[192:195], v[10:13]
	v_mfma_f32_16x16x32_bf16 v[62:65], v[140:143], v[172:175], v[62:65]
	v_mfma_f32_16x16x32_bf16 v[58:61], v[148:151], v[172:175], v[58:61]
	v_mfma_f32_16x16x32_bf16 v[46:49], v[140:143], v[180:183], v[46:49]
	v_mfma_f32_16x16x32_bf16 v[42:45], v[148:151], v[180:183], v[42:45]
	v_mfma_f32_16x16x32_bf16 v[30:33], v[140:143], v[188:191], v[30:33]
	v_mfma_f32_16x16x32_bf16 v[26:29], v[148:151], v[188:191], v[26:29]
	v_mfma_f32_16x16x32_bf16 v[14:17], v[140:143], v[196:199], v[14:17]
	v_mfma_f32_16x16x32_bf16 v[10:13], v[148:151], v[196:199], v[10:13]
	s_barrier
	s_add_u32 s50, s50, 0x80080
	s_addc_u32 s51, s51, 0
	s_add_i32 s52, s52, s54
	s_mov_b32 m0, s52
	s_nop 0
	global_load_lds_dwordx4 v0, s[50:51]
	s_add_i32 m0, s52, 0x2000
	s_nop 0
	global_load_lds_dwordx4 v130, s[50:51]
	s_add_u32 s0, s0, 0x100
	s_addc_u32 s1, s1, 0
	s_add_u32 s13, s13, 0x100
	s_addc_u32 s66, s66, 0
	s_mov_b32 s50, s67
	s_waitcnt vmcnt(6)
	s_barrier
	v_mfma_f32_16x16x32_bf16 v[54:57], v[224:227], v[168:171], v[54:57]
	v_mfma_f32_16x16x32_bf16 v[50:53], v[232:235], v[168:171], v[50:53]
	v_mfma_f32_16x16x32_bf16 v[38:41], v[224:227], v[176:179], v[38:41]
	v_mfma_f32_16x16x32_bf16 v[34:37], v[232:235], v[176:179], v[34:37]
	v_mfma_f32_16x16x32_bf16 v[22:25], v[224:227], v[184:187], v[22:25]
	v_mfma_f32_16x16x32_bf16 v[18:21], v[232:235], v[184:187], v[18:21]
	v_mfma_f32_16x16x32_bf16 v[6:9], v[224:227], v[192:195], v[6:9]
	v_mfma_f32_16x16x32_bf16 v[2:5], v[232:235], v[192:195], v[2:5]
	v_mfma_f32_16x16x32_bf16 v[54:57], v[228:231], v[172:175], v[54:57]
	v_mfma_f32_16x16x32_bf16 v[50:53], v[236:239], v[172:175], v[50:53]
	v_mfma_f32_16x16x32_bf16 v[38:41], v[228:231], v[180:183], v[38:41]
	v_mfma_f32_16x16x32_bf16 v[34:37], v[236:239], v[180:183], v[34:37]
	v_mfma_f32_16x16x32_bf16 v[22:25], v[228:231], v[188:191], v[22:25]
	v_mfma_f32_16x16x32_bf16 v[18:21], v[236:239], v[188:191], v[18:21]
	v_mfma_f32_16x16x32_bf16 v[6:9], v[228:231], v[196:199], v[6:9]
	v_mfma_f32_16x16x32_bf16 v[2:5], v[236:239], v[196:199], v[2:5]
	s_barrier
	s_cmp_ge_i32 s67, s41
	s_cbranch_scc0 .LBB0_282
	s_cmp_eq_u32 s63, 2
	s_cbranch_scc1 .Lepi6_orig
	v_readlane_b32 s90, v255, 17
	v_readlane_b32 s91, v255, 18
	v_readlane_b32 s96, v255, 19
	v_readlane_b32 s97, v255, 20
	v_readlane_b32 s8, v255, 25
	v_readlane_b32 s9, v255, 26
	v_readlane_b32 s68, v253, 58
	v_readlane_b32 s69, v253, 59
	v_lshl_or_b32 v156, s64, 8, v154
	v_lshlrev_b32_e32 v156, 2, v156
	v_lshl_add_u32 v157, v152, 13, v156
	s_lshl_b32 s72, s65, 21
	s_add_u32 s74, s68, s72
	s_addc_u32 s75, s69, 0
	s_add_u32 s76, s22, s72
	s_addc_u32 s77, s23, 0
	s_lshr_b32 s73, s65, 3
	s_mul_i32 s73, s73, 0xc000
	s_add_u32 s73, s73, 0x4000
	s_add_u32 s70, s90, s73
	s_addc_u32 s71, s91, 0
	global_load_dwordx4 v[140:143], v156, s[70:71]
	global_load_dwordx4 v[144:147], v156, s[70:71] offset:64
	global_load_dwordx4 v[148:151], v156, s[70:71] offset:512
	global_load_dwordx4 v[168:171], v156, s[70:71] offset:576
	global_load_dwordx4 v[224:227], v157, s[74:75] nt
	global_load_dwordx4 v[228:231], v157, s[74:75] offset:64 nt
	global_load_dwordx4 v[232:235], v157, s[74:75] offset:512 nt
	global_load_dwordx4 v[236:239], v157, s[74:75] offset:576 nt
	s_add_u32 s74, s74, 0x20000
	s_addc_u32 s75, s75, 0
	global_load_dwordx4 v[240:243], v157, s[74:75] nt
	global_load_dwordx4 v[244:247], v157, s[74:75] offset:64 nt
	s_waitcnt vmcnt(5)
	v_pk_fma_f32 v[128:129], v[128:129], v[142:143], v[226:227]
	v_pk_fma_f32 v[126:127], v[126:127], v[140:141], v[224:225]
	global_store_dwordx4 v157, v[126:129], s[76:77]
	global_load_dwordx4 v[224:227], v157, s[74:75] offset:512 nt
	s_waitcnt vmcnt(6)
	v_pk_fma_f32 v[124:125], v[124:125], v[146:147], v[230:231]
	v_pk_fma_f32 v[122:123], v[122:123], v[144:145], v[228:229]
	global_store_dwordx4 v157, v[122:125], s[76:77] offset:64
	global_load_dwordx4 v[228:231], v157, s[74:75] offset:576 nt
	s_waitcnt vmcnt(7)
	v_pk_fma_f32 v[120:121], v[120:121], v[150:151], v[234:235]
	v_pk_fma_f32 v[118:119], v[118:119], v[148:149], v[232:233]
	global_store_dwordx4 v157, v[118:121], s[76:77] offset:512
	s_add_u32 s74, s74, 0x20000
	s_addc_u32 s75, s75, 0
	global_load_dwordx4 v[232:235], v157, s[74:75] nt
	s_waitcnt vmcnt(8)
	v_pk_fma_f32 v[116:117], v[116:117], v[170:171], v[238:239]
	v_pk_fma_f32 v[114:115], v[114:115], v[168:169], v[236:237]
	global_store_dwordx4 v157, v[114:117], s[76:77] offset:576
	global_load_dwordx4 v[236:239], v157, s[74:75] offset:64 nt
	s_add_u32 s76, s76, 0x20000
	s_addc_u32 s77, s77, 0
	s_waitcnt vmcnt(9)
	v_pk_fma_f32 v[112:113], v[112:113], v[142:143], v[242:243]
	v_pk_fma_f32 v[110:111], v[110:111], v[140:141], v[240:241]
	global_store_dwordx4 v157, v[110:113], s[76:77]
	global_load_dwordx4 v[240:243], v157, s[74:75] offset:512 nt
	s_waitcnt vmcnt(10)
	v_pk_fma_f32 v[108:109], v[108:109], v[146:147], v[246:247]
	v_pk_fma_f32 v[106:107], v[106:107], v[144:145], v[244:245]
	global_store_dwordx4 v157, v[106:109], s[76:77] offset:64
	global_load_dwordx4 v[244:247], v157, s[74:75] offset:576 nt
	s_waitcnt vmcnt(10)
	v_pk_fma_f32 v[104:105], v[104:105], v[150:151], v[226:227]
	v_pk_fma_f32 v[102:103], v[102:103], v[148:149], v[224:225]
	global_store_dwordx4 v157, v[102:105], s[76:77] offset:512
	s_add_u32 s74, s74, 0x20000
	s_addc_u32 s75, s75, 0
	global_load_dwordx4 v[224:227], v157, s[74:75] nt
	s_waitcnt vmcnt(10)
	v_pk_fma_f32 v[100:101], v[100:101], v[170:171], v[230:231]
	v_pk_fma_f32 v[98:99], v[98:99], v[168:169], v[228:229]
	global_store_dwordx4 v157, v[98:101], s[76:77] offset:576
	global_load_dwordx4 v[228:231], v157, s[74:75] offset:64 nt
	s_add_u32 s76, s76, 0x20000
	s_addc_u32 s77, s77, 0
	s_waitcnt vmcnt(10)
	v_pk_fma_f32 v[96:97], v[96:97], v[142:143], v[234:235]
	v_pk_fma_f32 v[94:95], v[94:95], v[140:141], v[232:233]
	global_store_dwordx4 v157, v[94:97], s[76:77]
	global_load_dwordx4 v[232:235], v157, s[74:75] offset:512 nt
	s_waitcnt vmcnt(10)
	v_pk_fma_f32 v[92:93], v[92:93], v[146:147], v[238:239]
	v_pk_fma_f32 v[90:91], v[90:91], v[144:145], v[236:237]
	global_store_dwordx4 v157, v[90:93], s[76:77] offset:64
	global_load_dwordx4 v[236:239], v157, s[74:75] offset:576 nt
	s_waitcnt vmcnt(10)
	v_pk_fma_f32 v[88:89], v[88:89], v[150:151], v[242:243]
	v_pk_fma_f32 v[86:87], v[86:87], v[148:149], v[240:241]
	global_store_dwordx4 v157, v[86:89], s[76:77] offset:512
	s_add_u32 s74, s74, 0xa0000
	s_addc_u32 s75, s75, 0
	global_load_dwordx4 v[240:243], v157, s[74:75] nt
	s_waitcnt vmcnt(10)
	v_pk_fma_f32 v[84:85], v[84:85], v[170:171], v[246:247]
	v_pk_fma_f32 v[82:83], v[82:83], v[168:169], v[244:245]
	global_store_dwordx4 v157, v[82:85], s[76:77] offset:576
	global_load_dwordx4 v[244:247], v157, s[74:75] offset:64 nt
	s_add_u32 s76, s76, 0x20000
	s_addc_u32 s77, s77, 0
	s_waitcnt vmcnt(10)
	v_pk_fma_f32 v[80:81], v[80:81], v[142:143], v[226:227]
	v_pk_fma_f32 v[78:79], v[78:79], v[140:141], v[224:225]
	global_store_dwordx4 v157, v[78:81], s[76:77]
	global_load_dwordx4 v[224:227], v157, s[74:75] offset:512 nt
	s_waitcnt vmcnt(10)
	v_pk_fma_f32 v[76:77], v[76:77], v[146:147], v[230:231]
	v_pk_fma_f32 v[74:75], v[74:75], v[144:145], v[228:229]
	global_store_dwordx4 v157, v[74:77], s[76:77] offset:64
	global_load_dwordx4 v[228:231], v157, s[74:75] offset:576 nt
	s_waitcnt vmcnt(10)
	v_pk_fma_f32 v[72:73], v[72:73], v[150:151], v[234:235]
	v_pk_fma_f32 v[70:71], v[70:71], v[148:149], v[232:233]
	global_store_dwordx4 v157, v[70:73], s[76:77] offset:512
	s_add_u32 s74, s74, 0x20000
	s_addc_u32 s75, s75, 0
	global_load_dwordx4 v[232:235], v157, s[74:75] nt
	s_waitcnt vmcnt(10)
	v_pk_fma_f32 v[68:69], v[68:69], v[170:171], v[238:239]
	v_pk_fma_f32 v[66:67], v[66:67], v[168:169], v[236:237]
	global_store_dwordx4 v157, v[66:69], s[76:77] offset:576
	global_load_dwordx4 v[236:239], v157, s[74:75] offset:64 nt
	s_add_u32 s76, s76, 0xa0000
	s_addc_u32 s77, s77, 0
	s_waitcnt vmcnt(10)
	v_pk_fma_f32 v[64:65], v[64:65], v[142:143], v[242:243]
	v_pk_fma_f32 v[62:63], v[62:63], v[140:141], v[240:241]
	global_store_dwordx4 v157, v[62:65], s[76:77]
	global_load_dwordx4 v[240:243], v157, s[74:75] offset:512 nt
	s_waitcnt vmcnt(10)
	v_pk_fma_f32 v[60:61], v[60:61], v[146:147], v[246:247]
	v_pk_fma_f32 v[58:59], v[58:59], v[144:145], v[244:245]
	global_store_dwordx4 v157, v[58:61], s[76:77] offset:64
	global_load_dwordx4 v[244:247], v157, s[74:75] offset:576 nt
	s_waitcnt vmcnt(10)
	v_pk_fma_f32 v[56:57], v[56:57], v[150:151], v[226:227]
	v_pk_fma_f32 v[54:55], v[54:55], v[148:149], v[224:225]
	global_store_dwordx4 v157, v[54:57], s[76:77] offset:512
	s_add_u32 s74, s74, 0x20000
	s_addc_u32 s75, s75, 0
	global_load_dwordx4 v[224:227], v157, s[74:75] nt
	s_waitcnt vmcnt(10)
	v_pk_fma_f32 v[52:53], v[52:53], v[170:171], v[230:231]
	v_pk_fma_f32 v[50:51], v[50:51], v[168:169], v[228:229]
	global_store_dwordx4 v157, v[50:53], s[76:77] offset:576
	global_load_dwordx4 v[228:231], v157, s[74:75] offset:64 nt
	s_add_u32 s76, s76, 0x20000
	s_addc_u32 s77, s77, 0
	s_waitcnt vmcnt(10)
	v_pk_fma_f32 v[48:49], v[48:49], v[142:143], v[234:235]
	v_pk_fma_f32 v[46:47], v[46:47], v[140:141], v[232:233]
	global_store_dwordx4 v157, v[46:49], s[76:77]
	global_load_dwordx4 v[232:235], v157, s[74:75] offset:512 nt
	s_waitcnt vmcnt(10)
	v_pk_fma_f32 v[44:45], v[44:45], v[146:147], v[238:239]
	v_pk_fma_f32 v[42:43], v[42:43], v[144:145], v[236:237]
	global_store_dwordx4 v157, v[42:45], s[76:77] offset:64
	global_load_dwordx4 v[236:239], v157, s[74:75] offset:576 nt
	s_waitcnt vmcnt(10)
	v_pk_fma_f32 v[40:41], v[40:41], v[150:151], v[242:243]
	v_pk_fma_f32 v[38:39], v[38:39], v[148:149], v[240:241]
	global_store_dwordx4 v157, v[38:41], s[76:77] offset:512
	s_add_u32 s74, s74, 0x20000
	s_addc_u32 s75, s75, 0
	global_load_dwordx4 v[240:243], v157, s[74:75] nt
	s_waitcnt vmcnt(10)
	v_pk_fma_f32 v[36:37], v[36:37], v[170:171], v[246:247]
	v_pk_fma_f32 v[34:35], v[34:35], v[168:169], v[244:245]
	global_store_dwordx4 v157, v[34:37], s[76:77] offset:576
	global_load_dwordx4 v[244:247], v157, s[74:75] offset:64 nt
	s_add_u32 s76, s76, 0x20000
	s_addc_u32 s77, s77, 0
	s_waitcnt vmcnt(10)
	v_pk_fma_f32 v[32:33], v[32:33], v[142:143], v[226:227]
	v_pk_fma_f32 v[30:31], v[30:31], v[140:141], v[224:225]
	global_store_dwordx4 v157, v[30:33], s[76:77]
	global_load_dwordx4 v[224:227], v157, s[74:75] offset:512 nt
	s_waitcnt vmcnt(10)
	v_pk_fma_f32 v[28:29], v[28:29], v[146:147], v[230:231]
	v_pk_fma_f32 v[26:27], v[26:27], v[144:145], v[228:229]
	global_store_dwordx4 v157, v[26:29], s[76:77] offset:64
	global_load_dwordx4 v[228:231], v157, s[74:75] offset:576 nt
	s_waitcnt vmcnt(10)
	v_pk_fma_f32 v[24:25], v[24:25], v[150:151], v[234:235]
	v_pk_fma_f32 v[22:23], v[22:23], v[148:149], v[232:233]
	global_store_dwordx4 v157, v[22:25], s[76:77] offset:512
	s_waitcnt vmcnt(9)
	v_pk_fma_f32 v[20:21], v[20:21], v[170:171], v[238:239]
	v_pk_fma_f32 v[18:19], v[18:19], v[168:169], v[236:237]
	global_store_dwordx4 v157, v[18:21], s[76:77] offset:576
	s_add_u32 s76, s76, 0x20000
	s_addc_u32 s77, s77, 0
	s_waitcnt vmcnt(8)
	v_pk_fma_f32 v[16:17], v[16:17], v[142:143], v[242:243]
	v_pk_fma_f32 v[14:15], v[14:15], v[140:141], v[240:241]
	global_store_dwordx4 v157, v[14:17], s[76:77]
	s_waitcnt vmcnt(7)
	v_pk_fma_f32 v[12:13], v[12:13], v[146:147], v[246:247]
	v_pk_fma_f32 v[10:11], v[10:11], v[144:145], v[244:245]
	global_store_dwordx4 v157, v[10:13], s[76:77] offset:64
	s_waitcnt vmcnt(6)
	v_pk_fma_f32 v[8:9], v[8:9], v[150:151], v[226:227]
	v_pk_fma_f32 v[6:7], v[6:7], v[148:149], v[224:225]
	global_store_dwordx4 v157, v[6:9], s[76:77] offset:512
	s_waitcnt vmcnt(5)
	v_pk_fma_f32 v[4:5], v[4:5], v[170:171], v[230:231]
	v_pk_fma_f32 v[2:3], v[2:3], v[168:169], v[228:229]
	global_store_dwordx4 v157, v[2:5], s[76:77] offset:576
	s_branch .LBB0_269

.LBB0_572:
	s_add_u32 s41, s46, 0xfff80080
	s_addc_u32 s48, s47, -1
	s_add_i32 s64, 0, 0x10000
	v_add_u32_e32 v156, s64, v141
	ds_read_b128 v[144:147], v156
	ds_read_b128 v[148:151], v156 offset:1024
	ds_read_b128 v[152:155], v156 offset:2048
	ds_read_b128 v[168:171], v156 offset:3072
	s_cmp_eq_u32 s39, 28
	s_cselect_b32 s51, s43, s48
	s_cselect_b32 s50, s42, s41
	s_cselect_b32 s49, s45, s13
	s_cselect_b32 s48, s44, s12
	s_add_i32 m0, s54, 0xc000
	ds_read_b128 v[172:175], v143
	ds_read_b128 v[176:179], v143 offset:1024
	ds_read_b128 v[180:183], v143 offset:2048
	ds_read_b128 v[184:187], v143 offset:3072
	ds_read_b128 v[188:191], v143 offset:4096
	ds_read_b128 v[192:195], v143 offset:5120
	ds_read_b128 v[196:199], v143 offset:6144
	ds_read_b128 v[224:227], v143 offset:7168
	global_load_lds_dwordx4 v136, s[46:47]
	s_add_i32 m0, s54, 0xe000
	s_nop 0
	global_load_lds_dwordx4 v138, s[46:47]
	s_waitcnt lgkmcnt(8)
	s_barrier
	s_waitcnt lgkmcnt(0)
	v_mfma_f32_16x16x32_bf16 v[126:129], v[144:147], v[172:175], v[126:129]
	v_mfma_f32_16x16x32_bf16 v[122:125], v[152:155], v[172:175], v[122:125]
	v_mfma_f32_16x16x32_bf16 v[118:121], v[144:147], v[180:183], v[118:121]
	v_mfma_f32_16x16x32_bf16 v[114:117], v[152:155], v[180:183], v[114:117]
	v_mfma_f32_16x16x32_bf16 v[102:105], v[144:147], v[188:191], v[102:105]
	v_mfma_f32_16x16x32_bf16 v[98:101], v[152:155], v[188:191], v[98:101]
	v_mfma_f32_16x16x32_bf16 v[86:89], v[144:147], v[196:199], v[86:89]
	v_mfma_f32_16x16x32_bf16 v[82:85], v[152:155], v[196:199], v[82:85]
	v_mfma_f32_16x16x32_bf16 v[126:129], v[148:151], v[176:179], v[126:129]
	v_mfma_f32_16x16x32_bf16 v[122:125], v[168:171], v[176:179], v[122:125]
	v_mfma_f32_16x16x32_bf16 v[118:121], v[148:151], v[184:187], v[118:121]
	v_mfma_f32_16x16x32_bf16 v[114:117], v[168:171], v[184:187], v[114:117]
	v_mfma_f32_16x16x32_bf16 v[102:105], v[148:151], v[192:195], v[102:105]
	v_mfma_f32_16x16x32_bf16 v[98:101], v[168:171], v[192:195], v[98:101]
	v_mfma_f32_16x16x32_bf16 v[86:89], v[148:151], v[224:227], v[86:89]
	v_mfma_f32_16x16x32_bf16 v[82:85], v[168:171], v[224:227], v[82:85]
	s_barrier
	s_add_i32 s41, 0, 0x14000
	v_add_u32_e32 v156, s41, v141
	s_add_i32 s64, s64, s53
	ds_read_b128 v[228:231], v156
	ds_read_b128 v[232:235], v156 offset:1024
	ds_read_b128 v[236:239], v156 offset:2048
	ds_read_b128 v[240:243], v156 offset:3072
	s_add_u32 s76, s48, s94
	s_addc_u32 s77, s49, s95
	s_mov_b32 m0, s64
	s_nop 0
	global_load_lds_dwordx4 v0, s[48:49]
	s_add_i32 m0, s64, 0x2000
	s_nop 0
	global_load_lds_dwordx4 v134, s[48:49]
	s_mov_b32 m0, s54
	s_add_u32 s78, s50, s94
	s_addc_u32 s79, s51, s95
	s_barrier
	s_waitcnt lgkmcnt(0)
	v_mfma_f32_16x16x32_bf16 v[110:113], v[228:231], v[172:175], v[110:113]
	v_mfma_f32_16x16x32_bf16 v[106:109], v[236:239], v[172:175], v[106:109]
	v_mfma_f32_16x16x32_bf16 v[94:97], v[228:231], v[180:183], v[94:97]
	v_mfma_f32_16x16x32_bf16 v[90:93], v[236:239], v[180:183], v[90:93]
	v_mfma_f32_16x16x32_bf16 v[78:81], v[228:231], v[188:191], v[78:81]
	v_mfma_f32_16x16x32_bf16 v[74:77], v[236:239], v[188:191], v[74:77]
	v_mfma_f32_16x16x32_bf16 v[70:73], v[228:231], v[196:199], v[70:73]
	v_mfma_f32_16x16x32_bf16 v[66:69], v[236:239], v[196:199], v[66:69]
	v_mfma_f32_16x16x32_bf16 v[110:113], v[232:235], v[176:179], v[110:113]
	v_mfma_f32_16x16x32_bf16 v[106:109], v[240:243], v[176:179], v[106:109]
	v_mfma_f32_16x16x32_bf16 v[94:97], v[232:235], v[184:187], v[94:97]
	v_mfma_f32_16x16x32_bf16 v[90:93], v[240:243], v[184:187], v[90:93]
	v_mfma_f32_16x16x32_bf16 v[78:81], v[232:235], v[192:195], v[78:81]
	v_mfma_f32_16x16x32_bf16 v[74:77], v[240:243], v[192:195], v[74:77]
	v_mfma_f32_16x16x32_bf16 v[70:73], v[232:235], v[224:227], v[70:73]
	v_mfma_f32_16x16x32_bf16 v[66:69], v[240:243], v[224:227], v[66:69]
	s_barrier
	ds_read_b128 v[172:175], v143 offset:16384
	ds_read_b128 v[176:179], v143 offset:17408
	ds_read_b128 v[180:183], v143 offset:18432
	ds_read_b128 v[184:187], v143 offset:19456
	ds_read_b128 v[188:191], v143 offset:20480
	ds_read_b128 v[192:195], v143 offset:21504
	ds_read_b128 v[196:199], v143 offset:22528
	ds_read_b128 v[224:227], v143 offset:23552
	global_load_lds_dwordx4 v130, s[50:51]
	s_mov_b32 m0, s55
	s_nop 0
	global_load_lds_dwordx4 v132, s[50:51]
	s_barrier
	s_waitcnt lgkmcnt(0)
	v_mfma_f32_16x16x32_bf16 v[62:65], v[144:147], v[172:175], v[62:65]
	v_mfma_f32_16x16x32_bf16 v[58:61], v[152:155], v[172:175], v[58:61]
	v_mfma_f32_16x16x32_bf16 v[54:57], v[144:147], v[180:183], v[54:57]
	v_mfma_f32_16x16x32_bf16 v[50:53], v[152:155], v[180:183], v[50:53]
	v_mfma_f32_16x16x32_bf16 v[38:41], v[144:147], v[188:191], v[38:41]
	v_mfma_f32_16x16x32_bf16 v[34:37], v[152:155], v[188:191], v[34:37]
	v_mfma_f32_16x16x32_bf16 v[22:25], v[144:147], v[196:199], v[22:25]
	v_mfma_f32_16x16x32_bf16 v[18:21], v[152:155], v[196:199], v[18:21]
	v_mfma_f32_16x16x32_bf16 v[62:65], v[148:151], v[176:179], v[62:65]
	v_mfma_f32_16x16x32_bf16 v[58:61], v[168:171], v[176:179], v[58:61]
	v_mfma_f32_16x16x32_bf16 v[54:57], v[148:151], v[184:187], v[54:57]
	v_mfma_f32_16x16x32_bf16 v[50:53], v[168:171], v[184:187], v[50:53]
	v_mfma_f32_16x16x32_bf16 v[38:41], v[148:151], v[192:195], v[38:41]
	v_mfma_f32_16x16x32_bf16 v[34:37], v[168:171], v[192:195], v[34:37]
	v_mfma_f32_16x16x32_bf16 v[22:25], v[148:151], v[224:227], v[22:25]
	v_mfma_f32_16x16x32_bf16 v[18:21], v[168:171], v[224:227], v[18:21]
	s_barrier
	s_add_u32 s64, s48, 0x80000
	s_addc_u32 s65, s49, 0
	s_add_i32 s41, s41, s53
	s_mov_b32 m0, s41
	s_nop 0
	global_load_lds_dwordx4 v0, s[64:65]
	s_add_i32 m0, s41, 0x2000
	s_nop 0
	global_load_lds_dwordx4 v134, s[64:65]
	s_add_i32 s41, 0, 0x18000
	v_add_u32_e32 v161, s41, v141
	s_waitcnt vmcnt(6)
	s_barrier
	v_mfma_f32_16x16x32_bf16 v[46:49], v[228:231], v[172:175], v[46:49]
	v_mfma_f32_16x16x32_bf16 v[42:45], v[236:239], v[172:175], v[42:45]
	v_mfma_f32_16x16x32_bf16 v[30:33], v[228:231], v[180:183], v[30:33]
	v_mfma_f32_16x16x32_bf16 v[26:29], v[236:239], v[180:183], v[26:29]
	v_mfma_f32_16x16x32_bf16 v[14:17], v[228:231], v[188:191], v[14:17]
	v_mfma_f32_16x16x32_bf16 v[10:13], v[236:239], v[188:191], v[10:13]
	v_mfma_f32_16x16x32_bf16 v[6:9], v[228:231], v[196:199], v[6:9]
	v_mfma_f32_16x16x32_bf16 v[2:5], v[236:239], v[196:199], v[2:5]
	v_mfma_f32_16x16x32_bf16 v[46:49], v[232:235], v[176:179], v[46:49]
	v_mfma_f32_16x16x32_bf16 v[42:45], v[240:243], v[176:179], v[42:45]
	v_mfma_f32_16x16x32_bf16 v[30:33], v[232:235], v[184:187], v[30:33]
	v_mfma_f32_16x16x32_bf16 v[26:29], v[240:243], v[184:187], v[26:29]
	v_mfma_f32_16x16x32_bf16 v[14:17], v[232:235], v[192:195], v[14:17]
	v_mfma_f32_16x16x32_bf16 v[10:13], v[240:243], v[192:195], v[10:13]
	v_mfma_f32_16x16x32_bf16 v[6:9], v[232:235], v[224:227], v[6:9]
	v_mfma_f32_16x16x32_bf16 v[2:5], v[240:243], v[224:227], v[2:5]
	s_barrier
	ds_read_b128 v[144:147], v161
	ds_read_b128 v[148:151], v161 offset:1024
	ds_read_b128 v[152:155], v161 offset:2048
	ds_read_b128 v[168:171], v161 offset:3072
	s_add_u32 s50, s50, 0x80000
	s_addc_u32 s51, s51, 0
	s_mov_b32 m0, s56
	ds_read_b128 v[172:175], v143 offset:32768
	ds_read_b128 v[176:179], v143 offset:33792
	ds_read_b128 v[180:183], v143 offset:34816
	ds_read_b128 v[184:187], v143 offset:35840
	ds_read_b128 v[188:191], v143 offset:36864
	ds_read_b128 v[192:195], v143 offset:37888
	ds_read_b128 v[196:199], v143 offset:38912
	ds_read_b128 v[224:227], v143 offset:39936
	global_load_lds_dwordx4 v130, s[50:51]
	s_mov_b32 m0, s57
	s_nop 0
	global_load_lds_dwordx4 v132, s[50:51]
	s_waitcnt lgkmcnt(8)
	s_barrier
	s_waitcnt lgkmcnt(0)
	v_mfma_f32_16x16x32_bf16 v[126:129], v[144:147], v[172:175], v[126:129]
	v_mfma_f32_16x16x32_bf16 v[122:125], v[152:155], v[172:175], v[122:125]
	v_mfma_f32_16x16x32_bf16 v[118:121], v[144:147], v[180:183], v[118:121]
	v_mfma_f32_16x16x32_bf16 v[114:117], v[152:155], v[180:183], v[114:117]
	v_mfma_f32_16x16x32_bf16 v[102:105], v[144:147], v[188:191], v[102:105]
	v_mfma_f32_16x16x32_bf16 v[98:101], v[152:155], v[188:191], v[98:101]
	v_mfma_f32_16x16x32_bf16 v[86:89], v[144:147], v[196:199], v[86:89]
	v_mfma_f32_16x16x32_bf16 v[82:85], v[152:155], v[196:199], v[82:85]
	v_mfma_f32_16x16x32_bf16 v[126:129], v[148:151], v[176:179], v[126:129]
	v_mfma_f32_16x16x32_bf16 v[122:125], v[168:171], v[176:179], v[122:125]
	v_mfma_f32_16x16x32_bf16 v[118:121], v[148:151], v[184:187], v[118:121]
	v_mfma_f32_16x16x32_bf16 v[114:117], v[168:171], v[184:187], v[114:117]
	v_mfma_f32_16x16x32_bf16 v[102:105], v[148:151], v[192:195], v[102:105]
	v_mfma_f32_16x16x32_bf16 v[98:101], v[168:171], v[192:195], v[98:101]
	v_mfma_f32_16x16x32_bf16 v[86:89], v[148:151], v[224:227], v[86:89]
	v_mfma_f32_16x16x32_bf16 v[82:85], v[168:171], v[224:227], v[82:85]
	s_barrier
	s_add_i32 s50, 0, 0x1c000
	s_add_i32 s41, s41, s53
	v_add_u32_e32 v161, s50, v141
	s_mov_b32 m0, s41
	ds_read_b128 v[228:231], v161
	ds_read_b128 v[232:235], v161 offset:1024
	ds_read_b128 v[236:239], v161 offset:2048
	ds_read_b128 v[240:243], v161 offset:3072
	global_load_lds_dwordx4 v0, s[76:77]
	s_add_i32 m0, s41, 0x2000
	s_nop 0
	global_load_lds_dwordx4 v134, s[76:77]
	s_mov_b32 m0, s59
	s_barrier
	s_waitcnt lgkmcnt(0)
	v_mfma_f32_16x16x32_bf16 v[110:113], v[228:231], v[172:175], v[110:113]
	v_mfma_f32_16x16x32_bf16 v[106:109], v[236:239], v[172:175], v[106:109]
	v_mfma_f32_16x16x32_bf16 v[94:97], v[228:231], v[180:183], v[94:97]
	v_mfma_f32_16x16x32_bf16 v[90:93], v[236:239], v[180:183], v[90:93]
	v_mfma_f32_16x16x32_bf16 v[78:81], v[228:231], v[188:191], v[78:81]
	v_mfma_f32_16x16x32_bf16 v[74:77], v[236:239], v[188:191], v[74:77]
	v_mfma_f32_16x16x32_bf16 v[70:73], v[228:231], v[196:199], v[70:73]
	v_mfma_f32_16x16x32_bf16 v[66:69], v[236:239], v[196:199], v[66:69]
	v_mfma_f32_16x16x32_bf16 v[110:113], v[232:235], v[176:179], v[110:113]
	v_mfma_f32_16x16x32_bf16 v[106:109], v[240:243], v[176:179], v[106:109]
	v_mfma_f32_16x16x32_bf16 v[94:97], v[232:235], v[184:187], v[94:97]
	v_mfma_f32_16x16x32_bf16 v[90:93], v[240:243], v[184:187], v[90:93]
	v_mfma_f32_16x16x32_bf16 v[78:81], v[232:235], v[192:195], v[78:81]
	v_mfma_f32_16x16x32_bf16 v[74:77], v[240:243], v[192:195], v[74:77]
	v_mfma_f32_16x16x32_bf16 v[70:73], v[232:235], v[224:227], v[70:73]
	v_mfma_f32_16x16x32_bf16 v[66:69], v[240:243], v[224:227], v[66:69]
	s_barrier
	ds_read_b128 v[172:175], v143 offset:49152
	ds_read_b128 v[176:179], v143 offset:50176
	ds_read_b128 v[180:183], v143 offset:51200
	ds_read_b128 v[184:187], v143 offset:52224
	ds_read_b128 v[188:191], v143 offset:53248
	ds_read_b128 v[192:195], v143 offset:54272
	ds_read_b128 v[196:199], v143 offset:55296
	ds_read_b128 v[224:227], v143 offset:56320
	global_load_lds_dwordx4 v130, s[78:79]
	s_mov_b32 m0, s60
	s_nop 0
	global_load_lds_dwordx4 v132, s[78:79]
	s_barrier
	s_waitcnt lgkmcnt(0)
	v_mfma_f32_16x16x32_bf16 v[62:65], v[144:147], v[172:175], v[62:65]
	v_mfma_f32_16x16x32_bf16 v[58:61], v[152:155], v[172:175], v[58:61]
	v_mfma_f32_16x16x32_bf16 v[54:57], v[144:147], v[180:183], v[54:57]
	v_mfma_f32_16x16x32_bf16 v[50:53], v[152:155], v[180:183], v[50:53]
	v_mfma_f32_16x16x32_bf16 v[38:41], v[144:147], v[188:191], v[38:41]
	v_mfma_f32_16x16x32_bf16 v[34:37], v[152:155], v[188:191], v[34:37]
	v_mfma_f32_16x16x32_bf16 v[22:25], v[144:147], v[196:199], v[22:25]
	v_mfma_f32_16x16x32_bf16 v[18:21], v[152:155], v[196:199], v[18:21]
	v_mfma_f32_16x16x32_bf16 v[62:65], v[148:151], v[176:179], v[62:65]
	v_mfma_f32_16x16x32_bf16 v[58:61], v[168:171], v[176:179], v[58:61]
	v_mfma_f32_16x16x32_bf16 v[54:57], v[148:151], v[184:187], v[54:57]
	v_mfma_f32_16x16x32_bf16 v[50:53], v[168:171], v[184:187], v[50:53]
	v_mfma_f32_16x16x32_bf16 v[38:41], v[148:151], v[192:195], v[38:41]
	v_mfma_f32_16x16x32_bf16 v[34:37], v[168:171], v[192:195], v[34:37]
	v_mfma_f32_16x16x32_bf16 v[22:25], v[148:151], v[224:227], v[22:25]
	v_mfma_f32_16x16x32_bf16 v[18:21], v[168:171], v[224:227], v[18:21]
	s_barrier
	s_add_u32 s48, s48, 0x80080
	s_addc_u32 s49, s49, 0
	s_add_i32 s41, s50, s53
	s_mov_b32 m0, s41
	s_nop 0
	global_load_lds_dwordx4 v0, s[48:49]
	s_add_i32 m0, s41, 0x2000
	s_nop 0
	global_load_lds_dwordx4 v134, s[48:49]
	s_add_i32 s39, s39, 2
	s_add_u32 s46, s46, 0x100
	s_addc_u32 s47, s47, 0
	s_add_u32 s12, s12, 0x100
	s_addc_u32 s13, s13, 0
	s_waitcnt vmcnt(6)
	s_barrier
	v_mfma_f32_16x16x32_bf16 v[46:49], v[228:231], v[172:175], v[46:49]
	v_mfma_f32_16x16x32_bf16 v[42:45], v[236:239], v[172:175], v[42:45]
	v_mfma_f32_16x16x32_bf16 v[30:33], v[228:231], v[180:183], v[30:33]
	v_mfma_f32_16x16x32_bf16 v[26:29], v[236:239], v[180:183], v[26:29]
	v_mfma_f32_16x16x32_bf16 v[14:17], v[228:231], v[188:191], v[14:17]
	v_mfma_f32_16x16x32_bf16 v[10:13], v[236:239], v[188:191], v[10:13]
	v_mfma_f32_16x16x32_bf16 v[6:9], v[228:231], v[196:199], v[6:9]
	v_mfma_f32_16x16x32_bf16 v[2:5], v[236:239], v[196:199], v[2:5]
	v_mfma_f32_16x16x32_bf16 v[46:49], v[232:235], v[176:179], v[46:49]
	v_mfma_f32_16x16x32_bf16 v[42:45], v[240:243], v[176:179], v[42:45]
	v_mfma_f32_16x16x32_bf16 v[30:33], v[232:235], v[184:187], v[30:33]
	v_mfma_f32_16x16x32_bf16 v[26:29], v[240:243], v[184:187], v[26:29]
	v_mfma_f32_16x16x32_bf16 v[14:17], v[232:235], v[192:195], v[14:17]
	v_mfma_f32_16x16x32_bf16 v[10:13], v[240:243], v[192:195], v[10:13]
	v_mfma_f32_16x16x32_bf16 v[6:9], v[232:235], v[224:227], v[6:9]
	v_mfma_f32_16x16x32_bf16 v[2:5], v[240:243], v[224:227], v[2:5]
	s_barrier
	s_cmp_gt_u32 s39, 29
	s_cbranch_scc0 .LBB0_572
	s_cmp_lg_u32 s62, 0
	s_cbranch_scc0 .LBB0_575
	s_lshl_b32 s39, s61, 8
	s_mov_b64 s[12:13], 0
	s_branch .LBB0_576

.LBB0_788:
	s_add_u32 s39, s46, 0xfff80080
	s_addc_u32 s48, s47, -1
	s_add_i32 s64, 0, 0x10000
	v_add_u32_e32 v156, s64, v141
	ds_read_b128 v[144:147], v156
	ds_read_b128 v[148:151], v156 offset:1024
	ds_read_b128 v[152:155], v156 offset:2048
	ds_read_b128 v[168:171], v156 offset:3072
	s_cmp_eq_u32 s13, 28
	s_cselect_b32 s51, s43, s48
	s_cselect_b32 s50, s42, s39
	s_cselect_b32 s49, s45, s12
	s_cselect_b32 s48, s44, s1
	s_add_i32 m0, s54, 0xc000
	ds_read_b128 v[172:175], v143
	ds_read_b128 v[176:179], v143 offset:1024
	ds_read_b128 v[180:183], v143 offset:2048
	ds_read_b128 v[184:187], v143 offset:3072
	ds_read_b128 v[188:191], v143 offset:4096
	ds_read_b128 v[192:195], v143 offset:5120
	ds_read_b128 v[196:199], v143 offset:6144
	ds_read_b128 v[224:227], v143 offset:7168
	global_load_lds_dwordx4 v136, s[46:47]
	s_add_i32 m0, s54, 0xe000
	s_nop 0
	global_load_lds_dwordx4 v138, s[46:47]
	s_waitcnt lgkmcnt(8)
	s_barrier
	s_waitcnt lgkmcnt(0)
	v_mfma_f32_16x16x32_bf16 v[126:129], v[144:147], v[172:175], v[126:129]
	v_mfma_f32_16x16x32_bf16 v[122:125], v[152:155], v[172:175], v[122:125]
	v_mfma_f32_16x16x32_bf16 v[118:121], v[144:147], v[180:183], v[118:121]
	v_mfma_f32_16x16x32_bf16 v[114:117], v[152:155], v[180:183], v[114:117]
	v_mfma_f32_16x16x32_bf16 v[102:105], v[144:147], v[188:191], v[102:105]
	v_mfma_f32_16x16x32_bf16 v[98:101], v[152:155], v[188:191], v[98:101]
	v_mfma_f32_16x16x32_bf16 v[86:89], v[144:147], v[196:199], v[86:89]
	v_mfma_f32_16x16x32_bf16 v[82:85], v[152:155], v[196:199], v[82:85]
	v_mfma_f32_16x16x32_bf16 v[126:129], v[148:151], v[176:179], v[126:129]
	v_mfma_f32_16x16x32_bf16 v[122:125], v[168:171], v[176:179], v[122:125]
	v_mfma_f32_16x16x32_bf16 v[118:121], v[148:151], v[184:187], v[118:121]
	v_mfma_f32_16x16x32_bf16 v[114:117], v[168:171], v[184:187], v[114:117]
	v_mfma_f32_16x16x32_bf16 v[102:105], v[148:151], v[192:195], v[102:105]
	v_mfma_f32_16x16x32_bf16 v[98:101], v[168:171], v[192:195], v[98:101]
	v_mfma_f32_16x16x32_bf16 v[86:89], v[148:151], v[224:227], v[86:89]
	v_mfma_f32_16x16x32_bf16 v[82:85], v[168:171], v[224:227], v[82:85]
	s_barrier
	s_add_i32 s39, 0, 0x14000
	v_add_u32_e32 v156, s39, v141
	s_add_i32 s64, s64, s53
	ds_read_b128 v[228:231], v156
	ds_read_b128 v[232:235], v156 offset:1024
	ds_read_b128 v[236:239], v156 offset:2048
	ds_read_b128 v[240:243], v156 offset:3072
	s_add_u32 s76, s48, s94
	s_addc_u32 s77, s49, s95
	s_mov_b32 m0, s64
	s_nop 0
	global_load_lds_dwordx4 v0, s[48:49]
	s_add_i32 m0, s64, 0x2000
	s_nop 0
	global_load_lds_dwordx4 v134, s[48:49]
	s_mov_b32 m0, s54
	s_add_u32 s78, s50, s94
	s_addc_u32 s79, s51, s95
	s_barrier
	s_waitcnt lgkmcnt(0)
	v_mfma_f32_16x16x32_bf16 v[110:113], v[228:231], v[172:175], v[110:113]
	v_mfma_f32_16x16x32_bf16 v[106:109], v[236:239], v[172:175], v[106:109]
	v_mfma_f32_16x16x32_bf16 v[94:97], v[228:231], v[180:183], v[94:97]
	v_mfma_f32_16x16x32_bf16 v[90:93], v[236:239], v[180:183], v[90:93]
	v_mfma_f32_16x16x32_bf16 v[78:81], v[228:231], v[188:191], v[78:81]
	v_mfma_f32_16x16x32_bf16 v[74:77], v[236:239], v[188:191], v[74:77]
	v_mfma_f32_16x16x32_bf16 v[70:73], v[228:231], v[196:199], v[70:73]
	v_mfma_f32_16x16x32_bf16 v[66:69], v[236:239], v[196:199], v[66:69]
	v_mfma_f32_16x16x32_bf16 v[110:113], v[232:235], v[176:179], v[110:113]
	v_mfma_f32_16x16x32_bf16 v[106:109], v[240:243], v[176:179], v[106:109]
	v_mfma_f32_16x16x32_bf16 v[94:97], v[232:235], v[184:187], v[94:97]
	v_mfma_f32_16x16x32_bf16 v[90:93], v[240:243], v[184:187], v[90:93]
	v_mfma_f32_16x16x32_bf16 v[78:81], v[232:235], v[192:195], v[78:81]
	v_mfma_f32_16x16x32_bf16 v[74:77], v[240:243], v[192:195], v[74:77]
	v_mfma_f32_16x16x32_bf16 v[70:73], v[232:235], v[224:227], v[70:73]
	v_mfma_f32_16x16x32_bf16 v[66:69], v[240:243], v[224:227], v[66:69]
	s_barrier
	ds_read_b128 v[172:175], v143 offset:16384
	ds_read_b128 v[176:179], v143 offset:17408
	ds_read_b128 v[180:183], v143 offset:18432
	ds_read_b128 v[184:187], v143 offset:19456
	ds_read_b128 v[188:191], v143 offset:20480
	ds_read_b128 v[192:195], v143 offset:21504
	ds_read_b128 v[196:199], v143 offset:22528
	ds_read_b128 v[224:227], v143 offset:23552
	global_load_lds_dwordx4 v130, s[50:51]
	s_mov_b32 m0, s55
	s_nop 0
	global_load_lds_dwordx4 v132, s[50:51]
	s_barrier
	s_waitcnt lgkmcnt(0)
	v_mfma_f32_16x16x32_bf16 v[62:65], v[144:147], v[172:175], v[62:65]
	v_mfma_f32_16x16x32_bf16 v[58:61], v[152:155], v[172:175], v[58:61]
	v_mfma_f32_16x16x32_bf16 v[54:57], v[144:147], v[180:183], v[54:57]
	v_mfma_f32_16x16x32_bf16 v[50:53], v[152:155], v[180:183], v[50:53]
	v_mfma_f32_16x16x32_bf16 v[38:41], v[144:147], v[188:191], v[38:41]
	v_mfma_f32_16x16x32_bf16 v[34:37], v[152:155], v[188:191], v[34:37]
	v_mfma_f32_16x16x32_bf16 v[22:25], v[144:147], v[196:199], v[22:25]
	v_mfma_f32_16x16x32_bf16 v[18:21], v[152:155], v[196:199], v[18:21]
	v_mfma_f32_16x16x32_bf16 v[62:65], v[148:151], v[176:179], v[62:65]
	v_mfma_f32_16x16x32_bf16 v[58:61], v[168:171], v[176:179], v[58:61]
	v_mfma_f32_16x16x32_bf16 v[54:57], v[148:151], v[184:187], v[54:57]
	v_mfma_f32_16x16x32_bf16 v[50:53], v[168:171], v[184:187], v[50:53]
	v_mfma_f32_16x16x32_bf16 v[38:41], v[148:151], v[192:195], v[38:41]
	v_mfma_f32_16x16x32_bf16 v[34:37], v[168:171], v[192:195], v[34:37]
	v_mfma_f32_16x16x32_bf16 v[22:25], v[148:151], v[224:227], v[22:25]
	v_mfma_f32_16x16x32_bf16 v[18:21], v[168:171], v[224:227], v[18:21]
	s_barrier
	s_add_u32 s64, s48, 0x80000
	s_addc_u32 s65, s49, 0
	s_add_i32 s39, s39, s53
	s_mov_b32 m0, s39
	s_nop 0
	global_load_lds_dwordx4 v0, s[64:65]
	s_add_i32 m0, s39, 0x2000
	s_nop 0
	global_load_lds_dwordx4 v134, s[64:65]
	s_add_i32 s39, 0, 0x18000
	v_add_u32_e32 v161, s39, v141
	s_waitcnt vmcnt(6)
	s_barrier
	v_mfma_f32_16x16x32_bf16 v[46:49], v[228:231], v[172:175], v[46:49]
	v_mfma_f32_16x16x32_bf16 v[42:45], v[236:239], v[172:175], v[42:45]
	v_mfma_f32_16x16x32_bf16 v[30:33], v[228:231], v[180:183], v[30:33]
	v_mfma_f32_16x16x32_bf16 v[26:29], v[236:239], v[180:183], v[26:29]
	v_mfma_f32_16x16x32_bf16 v[14:17], v[228:231], v[188:191], v[14:17]
	v_mfma_f32_16x16x32_bf16 v[10:13], v[236:239], v[188:191], v[10:13]
	v_mfma_f32_16x16x32_bf16 v[6:9], v[228:231], v[196:199], v[6:9]
	v_mfma_f32_16x16x32_bf16 v[2:5], v[236:239], v[196:199], v[2:5]
	v_mfma_f32_16x16x32_bf16 v[46:49], v[232:235], v[176:179], v[46:49]
	v_mfma_f32_16x16x32_bf16 v[42:45], v[240:243], v[176:179], v[42:45]
	v_mfma_f32_16x16x32_bf16 v[30:33], v[232:235], v[184:187], v[30:33]
	v_mfma_f32_16x16x32_bf16 v[26:29], v[240:243], v[184:187], v[26:29]
	v_mfma_f32_16x16x32_bf16 v[14:17], v[232:235], v[192:195], v[14:17]
	v_mfma_f32_16x16x32_bf16 v[10:13], v[240:243], v[192:195], v[10:13]
	v_mfma_f32_16x16x32_bf16 v[6:9], v[232:235], v[224:227], v[6:9]
	v_mfma_f32_16x16x32_bf16 v[2:5], v[240:243], v[224:227], v[2:5]
	s_barrier
	ds_read_b128 v[144:147], v161
	ds_read_b128 v[148:151], v161 offset:1024
	ds_read_b128 v[152:155], v161 offset:2048
	ds_read_b128 v[168:171], v161 offset:3072
	s_add_u32 s50, s50, 0x80000
	s_addc_u32 s51, s51, 0
	s_mov_b32 m0, s56
	ds_read_b128 v[172:175], v143 offset:32768
	ds_read_b128 v[176:179], v143 offset:33792
	ds_read_b128 v[180:183], v143 offset:34816
	ds_read_b128 v[184:187], v143 offset:35840
	ds_read_b128 v[188:191], v143 offset:36864
	ds_read_b128 v[192:195], v143 offset:37888
	ds_read_b128 v[196:199], v143 offset:38912
	ds_read_b128 v[224:227], v143 offset:39936
	global_load_lds_dwordx4 v130, s[50:51]
	s_mov_b32 m0, s57
	s_nop 0
	global_load_lds_dwordx4 v132, s[50:51]
	s_waitcnt lgkmcnt(8)
	s_barrier
	s_waitcnt lgkmcnt(0)
	v_mfma_f32_16x16x32_bf16 v[126:129], v[144:147], v[172:175], v[126:129]
	v_mfma_f32_16x16x32_bf16 v[122:125], v[152:155], v[172:175], v[122:125]
	v_mfma_f32_16x16x32_bf16 v[118:121], v[144:147], v[180:183], v[118:121]
	v_mfma_f32_16x16x32_bf16 v[114:117], v[152:155], v[180:183], v[114:117]
	v_mfma_f32_16x16x32_bf16 v[102:105], v[144:147], v[188:191], v[102:105]
	v_mfma_f32_16x16x32_bf16 v[98:101], v[152:155], v[188:191], v[98:101]
	v_mfma_f32_16x16x32_bf16 v[86:89], v[144:147], v[196:199], v[86:89]
	v_mfma_f32_16x16x32_bf16 v[82:85], v[152:155], v[196:199], v[82:85]
	v_mfma_f32_16x16x32_bf16 v[126:129], v[148:151], v[176:179], v[126:129]
	v_mfma_f32_16x16x32_bf16 v[122:125], v[168:171], v[176:179], v[122:125]
	v_mfma_f32_16x16x32_bf16 v[118:121], v[148:151], v[184:187], v[118:121]
	v_mfma_f32_16x16x32_bf16 v[114:117], v[168:171], v[184:187], v[114:117]
	v_mfma_f32_16x16x32_bf16 v[102:105], v[148:151], v[192:195], v[102:105]
	v_mfma_f32_16x16x32_bf16 v[98:101], v[168:171], v[192:195], v[98:101]
	v_mfma_f32_16x16x32_bf16 v[86:89], v[148:151], v[224:227], v[86:89]
	v_mfma_f32_16x16x32_bf16 v[82:85], v[168:171], v[224:227], v[82:85]
	s_barrier
	s_add_i32 s50, 0, 0x1c000
	s_add_i32 s39, s39, s53
	v_add_u32_e32 v161, s50, v141
	s_mov_b32 m0, s39
	ds_read_b128 v[228:231], v161
	ds_read_b128 v[232:235], v161 offset:1024
	ds_read_b128 v[236:239], v161 offset:2048
	ds_read_b128 v[240:243], v161 offset:3072
	global_load_lds_dwordx4 v0, s[76:77]
	s_add_i32 m0, s39, 0x2000
	s_nop 0
	global_load_lds_dwordx4 v134, s[76:77]
	s_mov_b32 m0, s59
	s_barrier
	s_waitcnt lgkmcnt(0)
	v_mfma_f32_16x16x32_bf16 v[110:113], v[228:231], v[172:175], v[110:113]
	v_mfma_f32_16x16x32_bf16 v[106:109], v[236:239], v[172:175], v[106:109]
	v_mfma_f32_16x16x32_bf16 v[94:97], v[228:231], v[180:183], v[94:97]
	v_mfma_f32_16x16x32_bf16 v[90:93], v[236:239], v[180:183], v[90:93]
	v_mfma_f32_16x16x32_bf16 v[78:81], v[228:231], v[188:191], v[78:81]
	v_mfma_f32_16x16x32_bf16 v[74:77], v[236:239], v[188:191], v[74:77]
	v_mfma_f32_16x16x32_bf16 v[70:73], v[228:231], v[196:199], v[70:73]
	v_mfma_f32_16x16x32_bf16 v[66:69], v[236:239], v[196:199], v[66:69]
	v_mfma_f32_16x16x32_bf16 v[110:113], v[232:235], v[176:179], v[110:113]
	v_mfma_f32_16x16x32_bf16 v[106:109], v[240:243], v[176:179], v[106:109]
	v_mfma_f32_16x16x32_bf16 v[94:97], v[232:235], v[184:187], v[94:97]
	v_mfma_f32_16x16x32_bf16 v[90:93], v[240:243], v[184:187], v[90:93]
	v_mfma_f32_16x16x32_bf16 v[78:81], v[232:235], v[192:195], v[78:81]
	v_mfma_f32_16x16x32_bf16 v[74:77], v[240:243], v[192:195], v[74:77]
	v_mfma_f32_16x16x32_bf16 v[70:73], v[232:235], v[224:227], v[70:73]
	v_mfma_f32_16x16x32_bf16 v[66:69], v[240:243], v[224:227], v[66:69]
	s_barrier
	ds_read_b128 v[172:175], v143 offset:49152
	ds_read_b128 v[176:179], v143 offset:50176
	ds_read_b128 v[180:183], v143 offset:51200
	ds_read_b128 v[184:187], v143 offset:52224
	ds_read_b128 v[188:191], v143 offset:53248
	ds_read_b128 v[192:195], v143 offset:54272
	ds_read_b128 v[196:199], v143 offset:55296
	ds_read_b128 v[224:227], v143 offset:56320
	global_load_lds_dwordx4 v130, s[78:79]
	s_mov_b32 m0, s61
	s_nop 0
	global_load_lds_dwordx4 v132, s[78:79]
	s_barrier
	s_waitcnt lgkmcnt(0)
	v_mfma_f32_16x16x32_bf16 v[62:65], v[144:147], v[172:175], v[62:65]
	v_mfma_f32_16x16x32_bf16 v[58:61], v[152:155], v[172:175], v[58:61]
	v_mfma_f32_16x16x32_bf16 v[54:57], v[144:147], v[180:183], v[54:57]
	v_mfma_f32_16x16x32_bf16 v[50:53], v[152:155], v[180:183], v[50:53]
	v_mfma_f32_16x16x32_bf16 v[38:41], v[144:147], v[188:191], v[38:41]
	v_mfma_f32_16x16x32_bf16 v[34:37], v[152:155], v[188:191], v[34:37]
	v_mfma_f32_16x16x32_bf16 v[22:25], v[144:147], v[196:199], v[22:25]
	v_mfma_f32_16x16x32_bf16 v[18:21], v[152:155], v[196:199], v[18:21]
	v_mfma_f32_16x16x32_bf16 v[62:65], v[148:151], v[176:179], v[62:65]
	v_mfma_f32_16x16x32_bf16 v[58:61], v[168:171], v[176:179], v[58:61]
	v_mfma_f32_16x16x32_bf16 v[54:57], v[148:151], v[184:187], v[54:57]
	v_mfma_f32_16x16x32_bf16 v[50:53], v[168:171], v[184:187], v[50:53]
	v_mfma_f32_16x16x32_bf16 v[38:41], v[148:151], v[192:195], v[38:41]
	v_mfma_f32_16x16x32_bf16 v[34:37], v[168:171], v[192:195], v[34:37]
	v_mfma_f32_16x16x32_bf16 v[22:25], v[148:151], v[224:227], v[22:25]
	v_mfma_f32_16x16x32_bf16 v[18:21], v[168:171], v[224:227], v[18:21]
	s_barrier
	s_add_u32 s48, s48, 0x80080
	s_addc_u32 s49, s49, 0
	s_add_i32 s39, s50, s53
	s_mov_b32 m0, s39
	s_nop 0
	global_load_lds_dwordx4 v0, s[48:49]
	s_add_i32 m0, s39, 0x2000
	s_nop 0
	global_load_lds_dwordx4 v134, s[48:49]
	s_add_i32 s13, s13, 2
	s_add_u32 s46, s46, 0x100
	s_addc_u32 s47, s47, 0
	s_add_u32 s1, s1, 0x100
	s_addc_u32 s12, s12, 0
	s_waitcnt vmcnt(6)
	s_barrier
	v_mfma_f32_16x16x32_bf16 v[46:49], v[228:231], v[172:175], v[46:49]
	v_mfma_f32_16x16x32_bf16 v[42:45], v[236:239], v[172:175], v[42:45]
	v_mfma_f32_16x16x32_bf16 v[30:33], v[228:231], v[180:183], v[30:33]
	v_mfma_f32_16x16x32_bf16 v[26:29], v[236:239], v[180:183], v[26:29]
	v_mfma_f32_16x16x32_bf16 v[14:17], v[228:231], v[188:191], v[14:17]
	v_mfma_f32_16x16x32_bf16 v[10:13], v[236:239], v[188:191], v[10:13]
	v_mfma_f32_16x16x32_bf16 v[6:9], v[228:231], v[196:199], v[6:9]
	v_mfma_f32_16x16x32_bf16 v[2:5], v[236:239], v[196:199], v[2:5]
	v_mfma_f32_16x16x32_bf16 v[46:49], v[232:235], v[176:179], v[46:49]
	v_mfma_f32_16x16x32_bf16 v[42:45], v[240:243], v[176:179], v[42:45]
	v_mfma_f32_16x16x32_bf16 v[30:33], v[232:235], v[184:187], v[30:33]
	v_mfma_f32_16x16x32_bf16 v[26:29], v[240:243], v[184:187], v[26:29]
	v_mfma_f32_16x16x32_bf16 v[14:17], v[232:235], v[192:195], v[14:17]
	v_mfma_f32_16x16x32_bf16 v[10:13], v[240:243], v[192:195], v[10:13]
	v_mfma_f32_16x16x32_bf16 v[6:9], v[232:235], v[224:227], v[6:9]
	v_mfma_f32_16x16x32_bf16 v[2:5], v[240:243], v[224:227], v[2:5]
	s_barrier
	s_cmp_gt_u32 s13, 29
	s_cbranch_scc0 .LBB0_788
	s_cmp_lg_u32 s62, 0
	s_cbranch_scc0 .LBB0_791
	s_lshl_b32 s1, s60, 8
	s_mov_b64 s[12:13], 0
	s_branch .LBB0_792
